# snake order of the chained MFMA pairs (every pair reuses one operand fragment of the pair before it) in all live bf16 K-loops
# baseline (speedup 1.0000x reference)
.LBB0_1516:
	v_add_u32_e32 v156, s83, v142
	v_add_u32_e32 v172, s44, v142
	s_add_u32 s8, s37, s6
	ds_read_b128 v[144:147], v156
	ds_read_b128 v[148:151], v156 offset:1024
	ds_read_b128 v[152:155], v156 offset:2048
	ds_read_b128 v[156:159], v156 offset:3072
	ds_read_b128 v[160:163], v172
	ds_read_b128 v[164:167], v172 offset:1024
	ds_read_b128 v[168:171], v172 offset:2048
	ds_read_b128 v[172:175], v172 offset:3072
	s_addc_u32 s9, s40, s7
	s_add_u32 s8, s8, 0x20400100
	s_addc_u32 s9, s9, 0
	s_add_u32 s46, s41, s6
	s_addc_u32 s47, s42, s7
	s_cmpk_eq_i32 s6, 0xf00
	s_cselect_b32 s11, s5, s9
	s_cselect_b32 s10, s4, s8
	s_cselect_b32 s9, s3, s47
	s_cselect_b32 s8, s2, s46
	v_lshl_add_u64 v[208:209], v[138:139], 0, s[6:7]
	s_add_i32 m0, s16, 0xc000
	ds_read_b128 v[176:179], v143
	ds_read_b128 v[180:183], v143 offset:1024
	ds_read_b128 v[184:187], v143 offset:2048
	ds_read_b128 v[188:191], v143 offset:3072
	ds_read_b128 v[192:195], v143 offset:4096
	ds_read_b128 v[196:199], v143 offset:5120
	ds_read_b128 v[200:203], v143 offset:6144
	ds_read_b128 v[204:207], v143 offset:7168
	global_load_lds_dwordx4 v[208:209], off
	v_lshl_add_u64 v[208:209], v[140:141], 0, s[6:7]
	s_add_i32 m0, s16, 0xe000
	s_nop 0
	global_load_lds_dwordx4 v[208:209], off
	s_waitcnt vmcnt(8)
	s_waitcnt lgkmcnt(0)
	s_barrier
	s_setprio 1
	s_waitcnt lgkmcnt(0)
	v_mfma_f32_16x16x32_bf16 v[128:131], v[144:147], v[176:179], v[128:131]
	v_mfma_f32_16x16x32_bf16 v[128:131], v[148:151], v[180:183], v[128:131]
	v_mfma_f32_16x16x32_bf16 v[112:115], v[144:147], v[184:187], v[112:115]
	v_mfma_f32_16x16x32_bf16 v[112:115], v[148:151], v[188:191], v[112:115]
	v_mfma_f32_16x16x32_bf16 v[96:99], v[144:147], v[192:195], v[96:99]
	v_mfma_f32_16x16x32_bf16 v[96:99], v[148:151], v[196:199], v[96:99]
	v_mfma_f32_16x16x32_bf16 v[80:83], v[144:147], v[200:203], v[80:83]
	v_mfma_f32_16x16x32_bf16 v[80:83], v[148:151], v[204:207], v[80:83]
	v_mfma_f32_16x16x32_bf16 v[76:79], v[152:155], v[200:203], v[76:79]
	v_mfma_f32_16x16x32_bf16 v[76:79], v[156:159], v[204:207], v[76:79]
	v_mfma_f32_16x16x32_bf16 v[92:95], v[152:155], v[192:195], v[92:95]
	v_mfma_f32_16x16x32_bf16 v[92:95], v[156:159], v[196:199], v[92:95]
	v_mfma_f32_16x16x32_bf16 v[108:111], v[152:155], v[184:187], v[108:111]
	v_mfma_f32_16x16x32_bf16 v[108:111], v[156:159], v[188:191], v[108:111]
	v_mfma_f32_16x16x32_bf16 v[124:127], v[152:155], v[176:179], v[124:127]
	v_mfma_f32_16x16x32_bf16 v[124:127], v[156:159], v[180:183], v[124:127]
	s_setprio 0
	s_setprio 1
	v_mfma_f32_16x16x32_bf16 v[120:123], v[160:163], v[176:179], v[120:123]
	v_mfma_f32_16x16x32_bf16 v[120:123], v[164:167], v[180:183], v[120:123]
	v_mfma_f32_16x16x32_bf16 v[104:107], v[160:163], v[184:187], v[104:107]
	v_mfma_f32_16x16x32_bf16 v[104:107], v[164:167], v[188:191], v[104:107]
	v_mfma_f32_16x16x32_bf16 v[88:91], v[160:163], v[192:195], v[88:91]
	v_mfma_f32_16x16x32_bf16 v[88:91], v[164:167], v[196:199], v[88:91]
	v_mfma_f32_16x16x32_bf16 v[72:75], v[160:163], v[200:203], v[72:75]
	v_mfma_f32_16x16x32_bf16 v[72:75], v[164:167], v[204:207], v[72:75]
	v_mfma_f32_16x16x32_bf16 v[68:71], v[168:171], v[200:203], v[68:71]
	v_mfma_f32_16x16x32_bf16 v[68:71], v[172:175], v[204:207], v[68:71]
	v_mfma_f32_16x16x32_bf16 v[84:87], v[168:171], v[192:195], v[84:87]
	v_mfma_f32_16x16x32_bf16 v[84:87], v[172:175], v[196:199], v[84:87]
	v_mfma_f32_16x16x32_bf16 v[100:103], v[168:171], v[184:187], v[100:103]
	v_mfma_f32_16x16x32_bf16 v[100:103], v[172:175], v[188:191], v[100:103]
	v_mfma_f32_16x16x32_bf16 v[116:119], v[168:171], v[176:179], v[116:119]
	v_mfma_f32_16x16x32_bf16 v[116:119], v[172:175], v[180:183], v[116:119]
	s_setprio 0
	s_barrier
	s_mov_b32 m0, s13
	v_lshl_add_u64 v[208:209], s[8:9], 0, v[2:3]
	s_add_u32 s46, s8, 0x80000
	ds_read_b128 v[176:179], v143 offset:16384
	ds_read_b128 v[180:183], v143 offset:17408
	ds_read_b128 v[184:187], v143 offset:18432
	ds_read_b128 v[188:191], v143 offset:19456
	ds_read_b128 v[192:195], v143 offset:20480
	ds_read_b128 v[196:199], v143 offset:21504
	ds_read_b128 v[200:203], v143 offset:22528
	ds_read_b128 v[204:207], v143 offset:23552
	global_load_lds_dwordx4 v[208:209], off
	v_lshl_add_u64 v[210:211], s[8:9], 0, v[136:137]
	s_mov_b32 m0, s14
	s_addc_u32 s47, s9, 0
	global_load_lds_dwordx4 v[210:211], off
	v_lshl_add_u64 v[216:217], s[46:47], 0, v[2:3]
	s_mov_b32 m0, s15
	v_lshl_add_u64 v[218:219], s[10:11], 0, v[134:135]
	global_load_lds_dwordx4 v[216:217], off
	v_lshl_add_u64 v[216:217], s[46:47], 0, v[136:137]
	s_mov_b32 m0, s19
	s_nop 0
	global_load_lds_dwordx4 v[216:217], off
	v_lshl_add_u64 v[216:217], s[10:11], 0, v[132:133]
	s_mov_b32 m0, s16
	s_nop 0
	global_load_lds_dwordx4 v[216:217], off
	s_mov_b32 m0, s20
	s_nop 0
	global_load_lds_dwordx4 v[218:219], off
	s_waitcnt vmcnt(8)
	s_waitcnt lgkmcnt(0)
	s_barrier
	s_setprio 1
	s_waitcnt lgkmcnt(0)
	v_mfma_f32_16x16x32_bf16 v[64:67], v[144:147], v[176:179], v[64:67]
	v_mfma_f32_16x16x32_bf16 v[64:67], v[148:151], v[180:183], v[64:67]
	v_mfma_f32_16x16x32_bf16 v[48:51], v[144:147], v[184:187], v[48:51]
	v_mfma_f32_16x16x32_bf16 v[48:51], v[148:151], v[188:191], v[48:51]
	v_mfma_f32_16x16x32_bf16 v[32:35], v[144:147], v[192:195], v[32:35]
	v_mfma_f32_16x16x32_bf16 v[32:35], v[148:151], v[196:199], v[32:35]
	v_mfma_f32_16x16x32_bf16 v[16:19], v[144:147], v[200:203], v[16:19]
	v_mfma_f32_16x16x32_bf16 v[16:19], v[148:151], v[204:207], v[16:19]
	v_mfma_f32_16x16x32_bf16 v[12:15], v[152:155], v[200:203], v[12:15]
	v_mfma_f32_16x16x32_bf16 v[12:15], v[156:159], v[204:207], v[12:15]
	v_mfma_f32_16x16x32_bf16 v[28:31], v[152:155], v[192:195], v[28:31]
	v_mfma_f32_16x16x32_bf16 v[28:31], v[156:159], v[196:199], v[28:31]
	v_mfma_f32_16x16x32_bf16 v[44:47], v[152:155], v[184:187], v[44:47]
	v_mfma_f32_16x16x32_bf16 v[44:47], v[156:159], v[188:191], v[44:47]
	v_mfma_f32_16x16x32_bf16 v[60:63], v[152:155], v[176:179], v[60:63]
	v_mfma_f32_16x16x32_bf16 v[60:63], v[156:159], v[180:183], v[60:63]
	s_setprio 0
	s_setprio 1
	v_mfma_f32_16x16x32_bf16 v[56:59], v[160:163], v[176:179], v[56:59]
	v_mfma_f32_16x16x32_bf16 v[56:59], v[164:167], v[180:183], v[56:59]
	v_mfma_f32_16x16x32_bf16 v[40:43], v[160:163], v[184:187], v[40:43]
	v_mfma_f32_16x16x32_bf16 v[40:43], v[164:167], v[188:191], v[40:43]
	v_mfma_f32_16x16x32_bf16 v[24:27], v[160:163], v[192:195], v[24:27]
	v_mfma_f32_16x16x32_bf16 v[24:27], v[164:167], v[196:199], v[24:27]
	v_mfma_f32_16x16x32_bf16 v[8:11], v[160:163], v[200:203], v[8:11]
	v_mfma_f32_16x16x32_bf16 v[8:11], v[164:167], v[204:207], v[8:11]
	v_mfma_f32_16x16x32_bf16 v[4:7], v[168:171], v[200:203], v[4:7]
	v_mfma_f32_16x16x32_bf16 v[4:7], v[172:175], v[204:207], v[4:7]
	v_mfma_f32_16x16x32_bf16 v[20:23], v[168:171], v[192:195], v[20:23]
	v_mfma_f32_16x16x32_bf16 v[20:23], v[172:175], v[196:199], v[20:23]
	v_mfma_f32_16x16x32_bf16 v[36:39], v[168:171], v[184:187], v[36:39]
	v_mfma_f32_16x16x32_bf16 v[36:39], v[172:175], v[188:191], v[36:39]
	v_mfma_f32_16x16x32_bf16 v[52:55], v[168:171], v[176:179], v[52:55]
	v_mfma_f32_16x16x32_bf16 v[52:55], v[172:175], v[180:183], v[52:55]
	s_setprio 0
	s_barrier
	v_add_u32_e32 v156, s45, v142
	v_add_u32_e32 v172, s74, v142
	ds_read_b128 v[144:147], v156
	ds_read_b128 v[148:151], v156 offset:1024
	ds_read_b128 v[152:155], v156 offset:2048
	ds_read_b128 v[156:159], v156 offset:3072
	ds_read_b128 v[160:163], v172
	ds_read_b128 v[164:167], v172 offset:1024
	ds_read_b128 v[168:171], v172 offset:2048
	ds_read_b128 v[172:175], v172 offset:3072
	s_add_u32 s10, s10, 0x80000
	s_addc_u32 s11, s11, 0
	s_mov_b32 m0, s22
	v_lshl_add_u64 v[220:221], s[10:11], 0, v[132:133]
	ds_read_b128 v[176:179], v143 offset:32768
	ds_read_b128 v[180:183], v143 offset:33792
	ds_read_b128 v[184:187], v143 offset:34816
	ds_read_b128 v[188:191], v143 offset:35840
	ds_read_b128 v[192:195], v143 offset:36864
	ds_read_b128 v[196:199], v143 offset:37888
	ds_read_b128 v[200:203], v143 offset:38912
	ds_read_b128 v[204:207], v143 offset:39936
	global_load_lds_dwordx4 v[220:221], off
	v_lshl_add_u64 v[220:221], s[10:11], 0, v[134:135]
	s_mov_b32 m0, s23
	s_nop 0
	global_load_lds_dwordx4 v[220:221], off
	s_waitcnt vmcnt(8)
	s_waitcnt lgkmcnt(0)
	s_barrier
	s_setprio 1
	s_waitcnt lgkmcnt(0)
	v_mfma_f32_16x16x32_bf16 v[128:131], v[144:147], v[176:179], v[128:131]
	v_mfma_f32_16x16x32_bf16 v[128:131], v[148:151], v[180:183], v[128:131]
	v_mfma_f32_16x16x32_bf16 v[112:115], v[144:147], v[184:187], v[112:115]
	v_mfma_f32_16x16x32_bf16 v[112:115], v[148:151], v[188:191], v[112:115]
	v_mfma_f32_16x16x32_bf16 v[96:99], v[144:147], v[192:195], v[96:99]
	v_mfma_f32_16x16x32_bf16 v[96:99], v[148:151], v[196:199], v[96:99]
	v_mfma_f32_16x16x32_bf16 v[80:83], v[144:147], v[200:203], v[80:83]
	v_mfma_f32_16x16x32_bf16 v[80:83], v[148:151], v[204:207], v[80:83]
	v_mfma_f32_16x16x32_bf16 v[76:79], v[152:155], v[200:203], v[76:79]
	v_mfma_f32_16x16x32_bf16 v[76:79], v[156:159], v[204:207], v[76:79]
	v_mfma_f32_16x16x32_bf16 v[92:95], v[152:155], v[192:195], v[92:95]
	v_mfma_f32_16x16x32_bf16 v[92:95], v[156:159], v[196:199], v[92:95]
	v_mfma_f32_16x16x32_bf16 v[108:111], v[152:155], v[184:187], v[108:111]
	v_mfma_f32_16x16x32_bf16 v[108:111], v[156:159], v[188:191], v[108:111]
	v_mfma_f32_16x16x32_bf16 v[124:127], v[152:155], v[176:179], v[124:127]
	v_mfma_f32_16x16x32_bf16 v[124:127], v[156:159], v[180:183], v[124:127]
	s_setprio 0
	s_setprio 1
	v_mfma_f32_16x16x32_bf16 v[120:123], v[160:163], v[176:179], v[120:123]
	v_mfma_f32_16x16x32_bf16 v[120:123], v[164:167], v[180:183], v[120:123]
	v_mfma_f32_16x16x32_bf16 v[104:107], v[160:163], v[184:187], v[104:107]
	v_mfma_f32_16x16x32_bf16 v[104:107], v[164:167], v[188:191], v[104:107]
	v_mfma_f32_16x16x32_bf16 v[88:91], v[160:163], v[192:195], v[88:91]
	v_mfma_f32_16x16x32_bf16 v[88:91], v[164:167], v[196:199], v[88:91]
	v_mfma_f32_16x16x32_bf16 v[72:75], v[160:163], v[200:203], v[72:75]
	v_mfma_f32_16x16x32_bf16 v[72:75], v[164:167], v[204:207], v[72:75]
	v_mfma_f32_16x16x32_bf16 v[68:71], v[168:171], v[200:203], v[68:71]
	v_mfma_f32_16x16x32_bf16 v[68:71], v[172:175], v[204:207], v[68:71]
	v_mfma_f32_16x16x32_bf16 v[84:87], v[168:171], v[192:195], v[84:87]
	v_mfma_f32_16x16x32_bf16 v[84:87], v[172:175], v[196:199], v[84:87]
	v_mfma_f32_16x16x32_bf16 v[100:103], v[168:171], v[184:187], v[100:103]
	v_mfma_f32_16x16x32_bf16 v[100:103], v[172:175], v[188:191], v[100:103]
	v_mfma_f32_16x16x32_bf16 v[116:119], v[168:171], v[176:179], v[116:119]
	v_mfma_f32_16x16x32_bf16 v[116:119], v[172:175], v[180:183], v[116:119]
	s_setprio 0
	s_barrier
	s_mov_b32 m0, s24
	v_lshl_add_u64 v[208:209], v[208:209], 0, s[64:65]
	s_add_u32 s8, s8, 0x80080
	ds_read_b128 v[176:179], v143 offset:49152
	ds_read_b128 v[180:183], v143 offset:50176
	ds_read_b128 v[184:187], v143 offset:51200
	ds_read_b128 v[188:191], v143 offset:52224
	ds_read_b128 v[192:195], v143 offset:53248
	ds_read_b128 v[196:199], v143 offset:54272
	ds_read_b128 v[200:203], v143 offset:55296
	ds_read_b128 v[204:207], v143 offset:56320
	global_load_lds_dwordx4 v[208:209], off
	v_lshl_add_u64 v[208:209], v[210:211], 0, s[64:65]
	s_mov_b32 m0, s25
	s_addc_u32 s9, s9, 0
	global_load_lds_dwordx4 v[208:209], off
	v_lshl_add_u64 v[208:209], s[8:9], 0, v[2:3]
	s_mov_b32 m0, s34
	s_nop 0
	global_load_lds_dwordx4 v[208:209], off
	v_lshl_add_u64 v[208:209], s[8:9], 0, v[136:137]
	s_mov_b32 m0, s35
	s_nop 0
	global_load_lds_dwordx4 v[208:209], off
	v_lshl_add_u64 v[208:209], v[216:217], 0, s[64:65]
	s_mov_b32 m0, s26
	s_nop 0
	global_load_lds_dwordx4 v[208:209], off
	v_lshl_add_u64 v[208:209], v[218:219], 0, s[64:65]
	s_mov_b32 m0, s27
	s_nop 0
	global_load_lds_dwordx4 v[208:209], off
	s_waitcnt vmcnt(8)
	s_waitcnt lgkmcnt(0)
	s_barrier
	s_setprio 1
	s_waitcnt lgkmcnt(0)
	v_mfma_f32_16x16x32_bf16 v[64:67], v[144:147], v[176:179], v[64:67]
	v_mfma_f32_16x16x32_bf16 v[64:67], v[148:151], v[180:183], v[64:67]
	v_mfma_f32_16x16x32_bf16 v[48:51], v[144:147], v[184:187], v[48:51]
	v_mfma_f32_16x16x32_bf16 v[48:51], v[148:151], v[188:191], v[48:51]
	v_mfma_f32_16x16x32_bf16 v[32:35], v[144:147], v[192:195], v[32:35]
	v_mfma_f32_16x16x32_bf16 v[32:35], v[148:151], v[196:199], v[32:35]
	v_mfma_f32_16x16x32_bf16 v[16:19], v[144:147], v[200:203], v[16:19]
	v_mfma_f32_16x16x32_bf16 v[16:19], v[148:151], v[204:207], v[16:19]
	v_mfma_f32_16x16x32_bf16 v[12:15], v[152:155], v[200:203], v[12:15]
	v_mfma_f32_16x16x32_bf16 v[12:15], v[156:159], v[204:207], v[12:15]
	v_mfma_f32_16x16x32_bf16 v[28:31], v[152:155], v[192:195], v[28:31]
	v_mfma_f32_16x16x32_bf16 v[28:31], v[156:159], v[196:199], v[28:31]
	v_mfma_f32_16x16x32_bf16 v[44:47], v[152:155], v[184:187], v[44:47]
	v_mfma_f32_16x16x32_bf16 v[44:47], v[156:159], v[188:191], v[44:47]
	v_mfma_f32_16x16x32_bf16 v[60:63], v[152:155], v[176:179], v[60:63]
	v_mfma_f32_16x16x32_bf16 v[60:63], v[156:159], v[180:183], v[60:63]
	s_setprio 0
	s_setprio 1
	v_mfma_f32_16x16x32_bf16 v[56:59], v[160:163], v[176:179], v[56:59]
	v_mfma_f32_16x16x32_bf16 v[56:59], v[164:167], v[180:183], v[56:59]
	v_mfma_f32_16x16x32_bf16 v[40:43], v[160:163], v[184:187], v[40:43]
	v_mfma_f32_16x16x32_bf16 v[40:43], v[164:167], v[188:191], v[40:43]
	v_mfma_f32_16x16x32_bf16 v[24:27], v[160:163], v[192:195], v[24:27]
	v_mfma_f32_16x16x32_bf16 v[24:27], v[164:167], v[196:199], v[24:27]
	v_mfma_f32_16x16x32_bf16 v[8:11], v[160:163], v[200:203], v[8:11]
	v_mfma_f32_16x16x32_bf16 v[8:11], v[164:167], v[204:207], v[8:11]
	v_mfma_f32_16x16x32_bf16 v[4:7], v[168:171], v[200:203], v[4:7]
	v_mfma_f32_16x16x32_bf16 v[4:7], v[172:175], v[204:207], v[4:7]
	v_mfma_f32_16x16x32_bf16 v[20:23], v[168:171], v[192:195], v[20:23]
	v_mfma_f32_16x16x32_bf16 v[20:23], v[172:175], v[196:199], v[20:23]
	v_mfma_f32_16x16x32_bf16 v[36:39], v[168:171], v[184:187], v[36:39]
	v_mfma_f32_16x16x32_bf16 v[36:39], v[172:175], v[188:191], v[36:39]
	v_mfma_f32_16x16x32_bf16 v[52:55], v[168:171], v[176:179], v[52:55]
	v_mfma_f32_16x16x32_bf16 v[52:55], v[172:175], v[180:183], v[52:55]
	s_setprio 0
	s_barrier
	s_add_i32 s43, s43, 2
	s_add_u32 s6, s6, 0x100
	s_addc_u32 s7, s7, 0
	s_cmp_gt_u32 s43, 29
	s_cbranch_scc0 .LBB0_1516
	s_cmpk_lt_u32 s21, 0x100
	s_cbranch_scc0 .LBB0_1519
	s_barrier

.LBB0_1876:
	v_add_u32_e32 v2, s83, v144
	ds_read_b128 v[146:149], v2
	ds_read_b128 v[150:153], v2 offset:1024
	ds_read_b128 v[154:157], v2 offset:2048
	ds_read_b128 v[158:161], v2 offset:3072
	v_add_u32_e32 v2, s44, v144
	ds_read_b128 v[162:165], v2
	ds_read_b128 v[166:169], v2 offset:1024
	ds_read_b128 v[170:173], v2 offset:2048
	ds_read_b128 v[174:177], v2 offset:3072
	s_add_i32 s70, s18, 2
	s_add_u32 s71, s42, 0x80
	s_addc_u32 s19, s43, 0
	s_cmp_eq_u32 s57, s18
	s_cselect_b32 s18, s34, s71
	s_cselect_b32 s19, s35, s19
	s_cselect_b32 s77, s25, s69
	s_cselect_b32 s76, s24, s68
	v_lshl_add_u64 v[210:211], s[42:43], 0, v[140:141]
	s_add_i32 m0, s23, 0xc000
	ds_read_b128 v[178:181], v145
	ds_read_b128 v[182:185], v145 offset:1024
	ds_read_b128 v[186:189], v145 offset:2048
	ds_read_b128 v[190:193], v145 offset:3072
	ds_read_b128 v[194:197], v145 offset:4096
	ds_read_b128 v[198:201], v145 offset:5120
	ds_read_b128 v[202:205], v145 offset:6144
	ds_read_b128 v[206:209], v145 offset:7168
	global_load_lds_dwordx4 v[210:211], off
	v_lshl_add_u64 v[210:211], s[42:43], 0, v[142:143]
	s_add_i32 m0, s23, 0xe000
	s_nop 0
	global_load_lds_dwordx4 v[210:211], off
	s_waitcnt vmcnt(8)
	s_waitcnt lgkmcnt(0)
	s_barrier
	s_setprio 1
	s_waitcnt lgkmcnt(0)
	v_mfma_f32_16x16x32_bf16 v[120:123], v[146:149], v[178:181], v[120:123]
	v_mfma_f32_16x16x32_bf16 v[120:123], v[150:153], v[182:185], v[120:123]
	v_mfma_f32_16x16x32_bf16 v[112:115], v[146:149], v[186:189], v[112:115]
	v_mfma_f32_16x16x32_bf16 v[112:115], v[150:153], v[190:193], v[112:115]
	v_mfma_f32_16x16x32_bf16 v[96:99], v[146:149], v[194:197], v[96:99]
	v_mfma_f32_16x16x32_bf16 v[96:99], v[150:153], v[198:201], v[96:99]
	v_mfma_f32_16x16x32_bf16 v[80:83], v[146:149], v[202:205], v[80:83]
	v_mfma_f32_16x16x32_bf16 v[80:83], v[150:153], v[206:209], v[80:83]
	v_mfma_f32_16x16x32_bf16 v[76:79], v[154:157], v[202:205], v[76:79]
	v_mfma_f32_16x16x32_bf16 v[76:79], v[158:161], v[206:209], v[76:79]
	v_mfma_f32_16x16x32_bf16 v[92:95], v[154:157], v[194:197], v[92:95]
	v_mfma_f32_16x16x32_bf16 v[92:95], v[158:161], v[198:201], v[92:95]
	v_mfma_f32_16x16x32_bf16 v[108:111], v[154:157], v[186:189], v[108:111]
	v_mfma_f32_16x16x32_bf16 v[108:111], v[158:161], v[190:193], v[108:111]
	v_mfma_f32_16x16x32_bf16 v[128:131], v[154:157], v[178:181], v[128:131]
	v_mfma_f32_16x16x32_bf16 v[128:131], v[158:161], v[182:185], v[128:131]
	s_setprio 0
	s_setprio 1
	v_mfma_f32_16x16x32_bf16 v[124:127], v[162:165], v[178:181], v[124:127]
	v_mfma_f32_16x16x32_bf16 v[124:127], v[166:169], v[182:185], v[124:127]
	v_mfma_f32_16x16x32_bf16 v[104:107], v[162:165], v[186:189], v[104:107]
	v_mfma_f32_16x16x32_bf16 v[104:107], v[166:169], v[190:193], v[104:107]
	v_mfma_f32_16x16x32_bf16 v[88:91], v[162:165], v[194:197], v[88:91]
	v_mfma_f32_16x16x32_bf16 v[88:91], v[166:169], v[198:201], v[88:91]
	v_mfma_f32_16x16x32_bf16 v[72:75], v[162:165], v[202:205], v[72:75]
	v_mfma_f32_16x16x32_bf16 v[72:75], v[166:169], v[206:209], v[72:75]
	v_mfma_f32_16x16x32_bf16 v[68:71], v[170:173], v[202:205], v[68:71]
	v_mfma_f32_16x16x32_bf16 v[68:71], v[174:177], v[206:209], v[68:71]
	v_mfma_f32_16x16x32_bf16 v[84:87], v[170:173], v[194:197], v[84:87]
	v_mfma_f32_16x16x32_bf16 v[84:87], v[174:177], v[198:201], v[84:87]
	v_mfma_f32_16x16x32_bf16 v[100:103], v[170:173], v[186:189], v[100:103]
	v_mfma_f32_16x16x32_bf16 v[100:103], v[174:177], v[190:193], v[100:103]
	v_mfma_f32_16x16x32_bf16 v[116:119], v[170:173], v[178:181], v[116:119]
	v_mfma_f32_16x16x32_bf16 v[116:119], v[174:177], v[182:185], v[116:119]
	s_setprio 0
	s_barrier
	s_mov_b32 m0, s16
	v_lshl_add_u64 v[210:211], s[76:77], 0, v[134:135]
	v_lshl_add_u64 v[216:217], s[76:77], 0, v[138:139]
	s_add_u32 s76, s76, s4
	ds_read_b128 v[178:181], v145 offset:16384
	ds_read_b128 v[182:185], v145 offset:17408
	ds_read_b128 v[186:189], v145 offset:18432
	ds_read_b128 v[190:193], v145 offset:19456
	ds_read_b128 v[194:197], v145 offset:20480
	ds_read_b128 v[198:201], v145 offset:21504
	ds_read_b128 v[202:205], v145 offset:22528
	ds_read_b128 v[206:209], v145 offset:23552
	global_load_lds_dwordx4 v[210:211], off
	s_mov_b32 m0, s20
	s_addc_u32 s77, s77, s5
	global_load_lds_dwordx4 v[216:217], off
	v_lshl_add_u64 v[218:219], s[76:77], 0, v[134:135]
	s_mov_b32 m0, s21
	v_lshl_add_u64 v[220:221], s[76:77], 0, v[138:139]
	global_load_lds_dwordx4 v[218:219], off
	s_mov_b32 m0, s22
	v_lshl_add_u64 v[222:223], s[18:19], 0, v[132:133]
	global_load_lds_dwordx4 v[220:221], off
	s_mov_b32 m0, s23
	v_lshl_add_u64 v[224:225], s[18:19], 0, v[136:137]
	global_load_lds_dwordx4 v[222:223], off
	s_mov_b32 m0, s26
	s_nop 0
	global_load_lds_dwordx4 v[224:225], off
	s_waitcnt vmcnt(8)
	s_waitcnt lgkmcnt(0)
	s_barrier
	s_setprio 1
	s_waitcnt lgkmcnt(0)
	v_mfma_f32_16x16x32_bf16 v[64:67], v[146:149], v[178:181], v[64:67]
	v_mfma_f32_16x16x32_bf16 v[64:67], v[150:153], v[182:185], v[64:67]
	v_mfma_f32_16x16x32_bf16 v[48:51], v[146:149], v[186:189], v[48:51]
	v_mfma_f32_16x16x32_bf16 v[48:51], v[150:153], v[190:193], v[48:51]
	v_mfma_f32_16x16x32_bf16 v[32:35], v[146:149], v[194:197], v[32:35]
	v_mfma_f32_16x16x32_bf16 v[32:35], v[150:153], v[198:201], v[32:35]
	v_mfma_f32_16x16x32_bf16 v[16:19], v[146:149], v[202:205], v[16:19]
	v_mfma_f32_16x16x32_bf16 v[16:19], v[150:153], v[206:209], v[16:19]
	v_mfma_f32_16x16x32_bf16 v[12:15], v[154:157], v[202:205], v[12:15]
	v_mfma_f32_16x16x32_bf16 v[12:15], v[158:161], v[206:209], v[12:15]
	v_mfma_f32_16x16x32_bf16 v[28:31], v[154:157], v[194:197], v[28:31]
	v_mfma_f32_16x16x32_bf16 v[28:31], v[158:161], v[198:201], v[28:31]
	v_mfma_f32_16x16x32_bf16 v[44:47], v[154:157], v[186:189], v[44:47]
	v_mfma_f32_16x16x32_bf16 v[44:47], v[158:161], v[190:193], v[44:47]
	v_mfma_f32_16x16x32_bf16 v[60:63], v[154:157], v[178:181], v[60:63]
	v_mfma_f32_16x16x32_bf16 v[60:63], v[158:161], v[182:185], v[60:63]
	s_setprio 0
	s_setprio 1
	v_mfma_f32_16x16x32_bf16 v[56:59], v[162:165], v[178:181], v[56:59]
	v_mfma_f32_16x16x32_bf16 v[56:59], v[166:169], v[182:185], v[56:59]
	v_mfma_f32_16x16x32_bf16 v[40:43], v[162:165], v[186:189], v[40:43]
	v_mfma_f32_16x16x32_bf16 v[40:43], v[166:169], v[190:193], v[40:43]
	v_mfma_f32_16x16x32_bf16 v[24:27], v[162:165], v[194:197], v[24:27]
	v_mfma_f32_16x16x32_bf16 v[24:27], v[166:169], v[198:201], v[24:27]
	v_mfma_f32_16x16x32_bf16 v[8:11], v[162:165], v[202:205], v[8:11]
	v_mfma_f32_16x16x32_bf16 v[8:11], v[166:169], v[206:209], v[8:11]
	v_mfma_f32_16x16x32_bf16 v[4:7], v[170:173], v[202:205], v[4:7]
	v_mfma_f32_16x16x32_bf16 v[4:7], v[174:177], v[206:209], v[4:7]
	v_mfma_f32_16x16x32_bf16 v[20:23], v[170:173], v[194:197], v[20:23]
	v_mfma_f32_16x16x32_bf16 v[20:23], v[174:177], v[198:201], v[20:23]
	v_mfma_f32_16x16x32_bf16 v[36:39], v[170:173], v[186:189], v[36:39]
	v_mfma_f32_16x16x32_bf16 v[36:39], v[174:177], v[190:193], v[36:39]
	v_mfma_f32_16x16x32_bf16 v[52:55], v[170:173], v[178:181], v[52:55]
	v_mfma_f32_16x16x32_bf16 v[52:55], v[174:177], v[182:185], v[52:55]
	s_setprio 0
	s_barrier
	v_add_u32_e32 v2, s45, v144
	ds_read_b128 v[146:149], v2
	ds_read_b128 v[150:153], v2 offset:1024
	ds_read_b128 v[154:157], v2 offset:2048
	ds_read_b128 v[158:161], v2 offset:3072
	v_add_u32_e32 v2, s74, v144
	ds_read_b128 v[162:165], v2
	ds_read_b128 v[166:169], v2 offset:1024
	ds_read_b128 v[170:173], v2 offset:2048
	ds_read_b128 v[174:177], v2 offset:3072
	s_add_u32 s18, s18, s4
	s_addc_u32 s19, s19, s5
	s_mov_b32 m0, s27
	v_lshl_add_u64 v[226:227], s[18:19], 0, v[132:133]
	ds_read_b128 v[178:181], v145 offset:32768
	ds_read_b128 v[182:185], v145 offset:33792
	ds_read_b128 v[186:189], v145 offset:34816
	ds_read_b128 v[190:193], v145 offset:35840
	ds_read_b128 v[194:197], v145 offset:36864
	ds_read_b128 v[198:201], v145 offset:37888
	ds_read_b128 v[202:205], v145 offset:38912
	ds_read_b128 v[206:209], v145 offset:39936
	global_load_lds_dwordx4 v[226:227], off
	v_lshl_add_u64 v[226:227], s[18:19], 0, v[136:137]
	s_mov_b32 m0, s37
	s_nop 0
	global_load_lds_dwordx4 v[226:227], off
	s_waitcnt vmcnt(8)
	s_waitcnt lgkmcnt(0)
	s_barrier
	s_setprio 1
	s_waitcnt lgkmcnt(0)
	v_mfma_f32_16x16x32_bf16 v[120:123], v[146:149], v[178:181], v[120:123]
	v_mfma_f32_16x16x32_bf16 v[120:123], v[150:153], v[182:185], v[120:123]
	v_mfma_f32_16x16x32_bf16 v[112:115], v[146:149], v[186:189], v[112:115]
	v_mfma_f32_16x16x32_bf16 v[112:115], v[150:153], v[190:193], v[112:115]
	v_mfma_f32_16x16x32_bf16 v[96:99], v[146:149], v[194:197], v[96:99]
	v_mfma_f32_16x16x32_bf16 v[96:99], v[150:153], v[198:201], v[96:99]
	v_mfma_f32_16x16x32_bf16 v[80:83], v[146:149], v[202:205], v[80:83]
	v_mfma_f32_16x16x32_bf16 v[80:83], v[150:153], v[206:209], v[80:83]
	v_mfma_f32_16x16x32_bf16 v[76:79], v[154:157], v[202:205], v[76:79]
	v_mfma_f32_16x16x32_bf16 v[76:79], v[158:161], v[206:209], v[76:79]
	v_mfma_f32_16x16x32_bf16 v[92:95], v[154:157], v[194:197], v[92:95]
	v_mfma_f32_16x16x32_bf16 v[92:95], v[158:161], v[198:201], v[92:95]
	v_mfma_f32_16x16x32_bf16 v[108:111], v[154:157], v[186:189], v[108:111]
	v_mfma_f32_16x16x32_bf16 v[108:111], v[158:161], v[190:193], v[108:111]
	v_mfma_f32_16x16x32_bf16 v[128:131], v[154:157], v[178:181], v[128:131]
	v_mfma_f32_16x16x32_bf16 v[128:131], v[158:161], v[182:185], v[128:131]
	s_setprio 0
	s_setprio 1
	v_mfma_f32_16x16x32_bf16 v[124:127], v[162:165], v[178:181], v[124:127]
	v_mfma_f32_16x16x32_bf16 v[124:127], v[166:169], v[182:185], v[124:127]
	v_mfma_f32_16x16x32_bf16 v[104:107], v[162:165], v[186:189], v[104:107]
	v_mfma_f32_16x16x32_bf16 v[104:107], v[166:169], v[190:193], v[104:107]
	v_mfma_f32_16x16x32_bf16 v[88:91], v[162:165], v[194:197], v[88:91]
	v_mfma_f32_16x16x32_bf16 v[88:91], v[166:169], v[198:201], v[88:91]
	v_mfma_f32_16x16x32_bf16 v[72:75], v[162:165], v[202:205], v[72:75]
	v_mfma_f32_16x16x32_bf16 v[72:75], v[166:169], v[206:209], v[72:75]
	v_mfma_f32_16x16x32_bf16 v[68:71], v[170:173], v[202:205], v[68:71]
	v_mfma_f32_16x16x32_bf16 v[68:71], v[174:177], v[206:209], v[68:71]
	v_mfma_f32_16x16x32_bf16 v[84:87], v[170:173], v[194:197], v[84:87]
	v_mfma_f32_16x16x32_bf16 v[84:87], v[174:177], v[198:201], v[84:87]
	v_mfma_f32_16x16x32_bf16 v[100:103], v[170:173], v[186:189], v[100:103]
	v_mfma_f32_16x16x32_bf16 v[100:103], v[174:177], v[190:193], v[100:103]
	v_mfma_f32_16x16x32_bf16 v[116:119], v[170:173], v[178:181], v[116:119]
	v_mfma_f32_16x16x32_bf16 v[116:119], v[174:177], v[182:185], v[116:119]
	s_setprio 0
	s_barrier
	s_mov_b32 m0, s49
	v_lshl_add_u64 v[210:211], v[210:211], 0, s[64:65]
	ds_read_b128 v[178:181], v145 offset:49152
	ds_read_b128 v[182:185], v145 offset:50176
	ds_read_b128 v[186:189], v145 offset:51200
	ds_read_b128 v[190:193], v145 offset:52224
	ds_read_b128 v[194:197], v145 offset:53248
	ds_read_b128 v[198:201], v145 offset:54272
	ds_read_b128 v[202:205], v145 offset:55296
	ds_read_b128 v[206:209], v145 offset:56320
	global_load_lds_dwordx4 v[210:211], off
	v_lshl_add_u64 v[210:211], v[216:217], 0, s[64:65]
	s_mov_b32 m0, s50
	s_nop 0
	global_load_lds_dwordx4 v[210:211], off
	v_lshl_add_u64 v[210:211], v[218:219], 0, s[64:65]
	s_mov_b32 m0, s53
	s_nop 0
	global_load_lds_dwordx4 v[210:211], off
	v_lshl_add_u64 v[210:211], v[220:221], 0, s[64:65]
	s_mov_b32 m0, s56
	s_nop 0
	global_load_lds_dwordx4 v[210:211], off
	v_lshl_add_u64 v[210:211], v[222:223], 0, s[64:65]
	s_mov_b32 m0, s51
	s_nop 0
	global_load_lds_dwordx4 v[210:211], off
	v_lshl_add_u64 v[210:211], v[224:225], 0, s[64:65]
	s_mov_b32 m0, s52
	s_nop 0
	global_load_lds_dwordx4 v[210:211], off
	s_waitcnt vmcnt(8)
	s_waitcnt lgkmcnt(0)
	s_barrier
	s_setprio 1
	s_waitcnt lgkmcnt(0)
	v_mfma_f32_16x16x32_bf16 v[64:67], v[146:149], v[178:181], v[64:67]
	v_mfma_f32_16x16x32_bf16 v[64:67], v[150:153], v[182:185], v[64:67]
	v_mfma_f32_16x16x32_bf16 v[48:51], v[146:149], v[186:189], v[48:51]
	v_mfma_f32_16x16x32_bf16 v[48:51], v[150:153], v[190:193], v[48:51]
	v_mfma_f32_16x16x32_bf16 v[32:35], v[146:149], v[194:197], v[32:35]
	v_mfma_f32_16x16x32_bf16 v[32:35], v[150:153], v[198:201], v[32:35]
	v_mfma_f32_16x16x32_bf16 v[16:19], v[146:149], v[202:205], v[16:19]
	v_mfma_f32_16x16x32_bf16 v[16:19], v[150:153], v[206:209], v[16:19]
	v_mfma_f32_16x16x32_bf16 v[12:15], v[154:157], v[202:205], v[12:15]
	v_mfma_f32_16x16x32_bf16 v[12:15], v[158:161], v[206:209], v[12:15]
	v_mfma_f32_16x16x32_bf16 v[28:31], v[154:157], v[194:197], v[28:31]
	v_mfma_f32_16x16x32_bf16 v[28:31], v[158:161], v[198:201], v[28:31]
	v_mfma_f32_16x16x32_bf16 v[44:47], v[154:157], v[186:189], v[44:47]
	v_mfma_f32_16x16x32_bf16 v[44:47], v[158:161], v[190:193], v[44:47]
	v_mfma_f32_16x16x32_bf16 v[60:63], v[154:157], v[178:181], v[60:63]
	v_mfma_f32_16x16x32_bf16 v[60:63], v[158:161], v[182:185], v[60:63]
	s_setprio 0
	s_setprio 1
	v_mfma_f32_16x16x32_bf16 v[56:59], v[162:165], v[178:181], v[56:59]
	v_mfma_f32_16x16x32_bf16 v[56:59], v[166:169], v[182:185], v[56:59]
	v_mfma_f32_16x16x32_bf16 v[40:43], v[162:165], v[186:189], v[40:43]
	v_mfma_f32_16x16x32_bf16 v[40:43], v[166:169], v[190:193], v[40:43]
	v_mfma_f32_16x16x32_bf16 v[24:27], v[162:165], v[194:197], v[24:27]
	v_mfma_f32_16x16x32_bf16 v[24:27], v[166:169], v[198:201], v[24:27]
	v_mfma_f32_16x16x32_bf16 v[8:11], v[162:165], v[202:205], v[8:11]
	v_mfma_f32_16x16x32_bf16 v[8:11], v[166:169], v[206:209], v[8:11]
	v_mfma_f32_16x16x32_bf16 v[4:7], v[170:173], v[202:205], v[4:7]
	v_mfma_f32_16x16x32_bf16 v[4:7], v[174:177], v[206:209], v[4:7]
	v_mfma_f32_16x16x32_bf16 v[20:23], v[170:173], v[194:197], v[20:23]
	v_mfma_f32_16x16x32_bf16 v[20:23], v[174:177], v[198:201], v[20:23]
	v_mfma_f32_16x16x32_bf16 v[36:39], v[170:173], v[186:189], v[36:39]
	v_mfma_f32_16x16x32_bf16 v[36:39], v[174:177], v[190:193], v[36:39]
	v_mfma_f32_16x16x32_bf16 v[52:55], v[170:173], v[178:181], v[52:55]
	v_mfma_f32_16x16x32_bf16 v[52:55], v[174:177], v[182:185], v[52:55]
	s_setprio 0
	s_barrier
	s_add_u32 s42, s42, 0x100
	s_addc_u32 s43, s43, 0
	s_add_u32 s68, s68, 0x100
	s_addc_u32 s69, s69, 0
	s_cmp_ge_i32 s70, s46
	s_mov_b32 s18, s70
	s_cbranch_scc0 .LBB0_1876

.LBB0_2329:
	s_add_i32 s43, s12, 2
	v_add_u32_e32 v156, s83, v142
	v_add_u32_e32 v172, s44, v142
	s_add_u32 s10, s8, 0x100
	ds_read_b128 v[144:147], v156
	ds_read_b128 v[148:151], v156 offset:1024
	ds_read_b128 v[152:155], v156 offset:2048
	ds_read_b128 v[156:159], v156 offset:3072
	ds_read_b128 v[160:163], v172
	ds_read_b128 v[164:167], v172 offset:1024
	ds_read_b128 v[168:171], v172 offset:2048
	ds_read_b128 v[172:175], v172 offset:3072
	s_addc_u32 s11, s9, 0
	s_cmp_lg_u32 s42, s12
	s_cselect_b32 s46, s10, 0
	s_cselect_b32 s47, s11, 0
	s_add_u32 s12, s6, s46
	s_addc_u32 s13, s7, s47
	s_add_u32 s46, s4, s46
	s_addc_u32 s47, s5, s47
	v_lshl_add_u64 v[208:209], v[138:139], 0, s[8:9]
	s_add_i32 m0, s22, 0xc000
	ds_read_b128 v[176:179], v143
	ds_read_b128 v[180:183], v143 offset:1024
	ds_read_b128 v[184:187], v143 offset:2048
	ds_read_b128 v[188:191], v143 offset:3072
	ds_read_b128 v[192:195], v143 offset:4096
	ds_read_b128 v[196:199], v143 offset:5120
	ds_read_b128 v[200:203], v143 offset:6144
	ds_read_b128 v[204:207], v143 offset:7168
	global_load_lds_dwordx4 v[208:209], off
	v_lshl_add_u64 v[208:209], v[140:141], 0, s[8:9]
	s_add_i32 m0, s22, 0xe000
	s_nop 0
	global_load_lds_dwordx4 v[208:209], off
	s_waitcnt vmcnt(8)
	s_waitcnt lgkmcnt(0)
	s_barrier
	s_setprio 1
	s_waitcnt lgkmcnt(0)
	v_mfma_f32_16x16x32_bf16 v[124:127], v[144:147], v[176:179], v[124:127]
	v_mfma_f32_16x16x32_bf16 v[124:127], v[148:151], v[180:183], v[124:127]
	v_mfma_f32_16x16x32_bf16 v[112:115], v[144:147], v[184:187], v[112:115]
	v_mfma_f32_16x16x32_bf16 v[112:115], v[148:151], v[188:191], v[112:115]
	v_mfma_f32_16x16x32_bf16 v[96:99], v[144:147], v[192:195], v[96:99]
	v_mfma_f32_16x16x32_bf16 v[96:99], v[148:151], v[196:199], v[96:99]
	v_mfma_f32_16x16x32_bf16 v[80:83], v[144:147], v[200:203], v[80:83]
	v_mfma_f32_16x16x32_bf16 v[80:83], v[148:151], v[204:207], v[80:83]
	v_mfma_f32_16x16x32_bf16 v[76:79], v[152:155], v[200:203], v[76:79]
	v_mfma_f32_16x16x32_bf16 v[76:79], v[156:159], v[204:207], v[76:79]
	v_mfma_f32_16x16x32_bf16 v[92:95], v[152:155], v[192:195], v[92:95]
	v_mfma_f32_16x16x32_bf16 v[92:95], v[156:159], v[196:199], v[92:95]
	v_mfma_f32_16x16x32_bf16 v[108:111], v[152:155], v[184:187], v[108:111]
	v_mfma_f32_16x16x32_bf16 v[108:111], v[156:159], v[188:191], v[108:111]
	v_mfma_f32_16x16x32_bf16 v[128:131], v[152:155], v[176:179], v[128:131]
	v_mfma_f32_16x16x32_bf16 v[128:131], v[156:159], v[180:183], v[128:131]
	s_setprio 0
	s_setprio 1
	v_mfma_f32_16x16x32_bf16 v[120:123], v[160:163], v[176:179], v[120:123]
	v_mfma_f32_16x16x32_bf16 v[120:123], v[164:167], v[180:183], v[120:123]
	v_mfma_f32_16x16x32_bf16 v[104:107], v[160:163], v[184:187], v[104:107]
	v_mfma_f32_16x16x32_bf16 v[104:107], v[164:167], v[188:191], v[104:107]
	v_mfma_f32_16x16x32_bf16 v[88:91], v[160:163], v[192:195], v[88:91]
	v_mfma_f32_16x16x32_bf16 v[88:91], v[164:167], v[196:199], v[88:91]
	v_mfma_f32_16x16x32_bf16 v[72:75], v[160:163], v[200:203], v[72:75]
	v_mfma_f32_16x16x32_bf16 v[72:75], v[164:167], v[204:207], v[72:75]
	v_mfma_f32_16x16x32_bf16 v[68:71], v[168:171], v[200:203], v[68:71]
	v_mfma_f32_16x16x32_bf16 v[68:71], v[172:175], v[204:207], v[68:71]
	v_mfma_f32_16x16x32_bf16 v[84:87], v[168:171], v[192:195], v[84:87]
	v_mfma_f32_16x16x32_bf16 v[84:87], v[172:175], v[196:199], v[84:87]
	v_mfma_f32_16x16x32_bf16 v[100:103], v[168:171], v[184:187], v[100:103]
	v_mfma_f32_16x16x32_bf16 v[100:103], v[172:175], v[188:191], v[100:103]
	v_mfma_f32_16x16x32_bf16 v[116:119], v[168:171], v[176:179], v[116:119]
	v_mfma_f32_16x16x32_bf16 v[116:119], v[172:175], v[180:183], v[116:119]
	s_setprio 0
	s_barrier
	s_mov_b32 m0, s18
	v_lshl_add_u64 v[208:209], s[46:47], 0, v[2:3]
	s_add_u32 s8, s46, s2
	ds_read_b128 v[176:179], v143 offset:16384
	ds_read_b128 v[180:183], v143 offset:17408
	ds_read_b128 v[184:187], v143 offset:18432
	ds_read_b128 v[188:191], v143 offset:19456
	ds_read_b128 v[192:195], v143 offset:20480
	ds_read_b128 v[196:199], v143 offset:21504
	ds_read_b128 v[200:203], v143 offset:22528
	ds_read_b128 v[204:207], v143 offset:23552
	global_load_lds_dwordx4 v[208:209], off
	v_lshl_add_u64 v[210:211], s[46:47], 0, v[136:137]
	s_mov_b32 m0, s19
	s_addc_u32 s9, s47, s3
	global_load_lds_dwordx4 v[210:211], off
	v_lshl_add_u64 v[216:217], s[8:9], 0, v[2:3]
	s_mov_b32 m0, s20
	v_lshl_add_u64 v[218:219], s[8:9], 0, v[136:137]
	global_load_lds_dwordx4 v[216:217], off
	s_mov_b32 m0, s21
	v_lshl_add_u64 v[220:221], s[12:13], 0, v[132:133]
	global_load_lds_dwordx4 v[218:219], off
	s_mov_b32 m0, s22
	v_lshl_add_u64 v[222:223], s[12:13], 0, v[134:135]
	global_load_lds_dwordx4 v[220:221], off
	s_mov_b32 m0, s23
	s_nop 0
	global_load_lds_dwordx4 v[222:223], off
	s_waitcnt vmcnt(8)
	s_waitcnt lgkmcnt(0)
	s_barrier
	s_setprio 1
	s_waitcnt lgkmcnt(0)
	v_mfma_f32_16x16x32_bf16 v[64:67], v[144:147], v[176:179], v[64:67]
	v_mfma_f32_16x16x32_bf16 v[64:67], v[148:151], v[180:183], v[64:67]
	v_mfma_f32_16x16x32_bf16 v[48:51], v[144:147], v[184:187], v[48:51]
	v_mfma_f32_16x16x32_bf16 v[48:51], v[148:151], v[188:191], v[48:51]
	v_mfma_f32_16x16x32_bf16 v[32:35], v[144:147], v[192:195], v[32:35]
	v_mfma_f32_16x16x32_bf16 v[32:35], v[148:151], v[196:199], v[32:35]
	v_mfma_f32_16x16x32_bf16 v[16:19], v[144:147], v[200:203], v[16:19]
	v_mfma_f32_16x16x32_bf16 v[16:19], v[148:151], v[204:207], v[16:19]
	v_mfma_f32_16x16x32_bf16 v[12:15], v[152:155], v[200:203], v[12:15]
	v_mfma_f32_16x16x32_bf16 v[12:15], v[156:159], v[204:207], v[12:15]
	v_mfma_f32_16x16x32_bf16 v[28:31], v[152:155], v[192:195], v[28:31]
	v_mfma_f32_16x16x32_bf16 v[28:31], v[156:159], v[196:199], v[28:31]
	v_mfma_f32_16x16x32_bf16 v[44:47], v[152:155], v[184:187], v[44:47]
	v_mfma_f32_16x16x32_bf16 v[44:47], v[156:159], v[188:191], v[44:47]
	v_mfma_f32_16x16x32_bf16 v[60:63], v[152:155], v[176:179], v[60:63]
	v_mfma_f32_16x16x32_bf16 v[60:63], v[156:159], v[180:183], v[60:63]
	s_setprio 0
	s_setprio 1
	v_mfma_f32_16x16x32_bf16 v[56:59], v[160:163], v[176:179], v[56:59]
	v_mfma_f32_16x16x32_bf16 v[56:59], v[164:167], v[180:183], v[56:59]
	v_mfma_f32_16x16x32_bf16 v[40:43], v[160:163], v[184:187], v[40:43]
	v_mfma_f32_16x16x32_bf16 v[40:43], v[164:167], v[188:191], v[40:43]
	v_mfma_f32_16x16x32_bf16 v[24:27], v[160:163], v[192:195], v[24:27]
	v_mfma_f32_16x16x32_bf16 v[24:27], v[164:167], v[196:199], v[24:27]
	v_mfma_f32_16x16x32_bf16 v[8:11], v[160:163], v[200:203], v[8:11]
	v_mfma_f32_16x16x32_bf16 v[8:11], v[164:167], v[204:207], v[8:11]
	v_mfma_f32_16x16x32_bf16 v[4:7], v[168:171], v[200:203], v[4:7]
	v_mfma_f32_16x16x32_bf16 v[4:7], v[172:175], v[204:207], v[4:7]
	v_mfma_f32_16x16x32_bf16 v[20:23], v[168:171], v[192:195], v[20:23]
	v_mfma_f32_16x16x32_bf16 v[20:23], v[172:175], v[196:199], v[20:23]
	v_mfma_f32_16x16x32_bf16 v[36:39], v[168:171], v[184:187], v[36:39]
	v_mfma_f32_16x16x32_bf16 v[36:39], v[172:175], v[188:191], v[36:39]
	v_mfma_f32_16x16x32_bf16 v[52:55], v[168:171], v[176:179], v[52:55]
	v_mfma_f32_16x16x32_bf16 v[52:55], v[172:175], v[180:183], v[52:55]
	s_setprio 0
	s_barrier
	v_add_u32_e32 v156, s45, v142
	v_add_u32_e32 v172, s74, v142
	ds_read_b128 v[144:147], v156
	ds_read_b128 v[148:151], v156 offset:1024
	ds_read_b128 v[152:155], v156 offset:2048
	ds_read_b128 v[156:159], v156 offset:3072
	ds_read_b128 v[160:163], v172
	ds_read_b128 v[164:167], v172 offset:1024
	ds_read_b128 v[168:171], v172 offset:2048
	ds_read_b128 v[172:175], v172 offset:3072
	s_add_u32 s8, s12, s2
	s_addc_u32 s9, s13, s3
	s_mov_b32 m0, s24
	v_lshl_add_u64 v[224:225], s[8:9], 0, v[132:133]
	ds_read_b128 v[176:179], v143 offset:32768
	ds_read_b128 v[180:183], v143 offset:33792
	ds_read_b128 v[184:187], v143 offset:34816
	ds_read_b128 v[188:191], v143 offset:35840
	ds_read_b128 v[192:195], v143 offset:36864
	ds_read_b128 v[196:199], v143 offset:37888
	ds_read_b128 v[200:203], v143 offset:38912
	ds_read_b128 v[204:207], v143 offset:39936
	global_load_lds_dwordx4 v[224:225], off
	v_lshl_add_u64 v[224:225], s[8:9], 0, v[134:135]
	s_mov_b32 m0, s25
	s_nop 0
	global_load_lds_dwordx4 v[224:225], off
	s_waitcnt vmcnt(8)
	s_waitcnt lgkmcnt(0)
	s_barrier
	s_setprio 1
	s_waitcnt lgkmcnt(0)
	v_mfma_f32_16x16x32_bf16 v[124:127], v[144:147], v[176:179], v[124:127]
	v_mfma_f32_16x16x32_bf16 v[124:127], v[148:151], v[180:183], v[124:127]
	v_mfma_f32_16x16x32_bf16 v[112:115], v[144:147], v[184:187], v[112:115]
	v_mfma_f32_16x16x32_bf16 v[112:115], v[148:151], v[188:191], v[112:115]
	v_mfma_f32_16x16x32_bf16 v[96:99], v[144:147], v[192:195], v[96:99]
	v_mfma_f32_16x16x32_bf16 v[96:99], v[148:151], v[196:199], v[96:99]
	v_mfma_f32_16x16x32_bf16 v[80:83], v[144:147], v[200:203], v[80:83]
	v_mfma_f32_16x16x32_bf16 v[80:83], v[148:151], v[204:207], v[80:83]
	v_mfma_f32_16x16x32_bf16 v[76:79], v[152:155], v[200:203], v[76:79]
	v_mfma_f32_16x16x32_bf16 v[76:79], v[156:159], v[204:207], v[76:79]
	v_mfma_f32_16x16x32_bf16 v[92:95], v[152:155], v[192:195], v[92:95]
	v_mfma_f32_16x16x32_bf16 v[92:95], v[156:159], v[196:199], v[92:95]
	v_mfma_f32_16x16x32_bf16 v[108:111], v[152:155], v[184:187], v[108:111]
	v_mfma_f32_16x16x32_bf16 v[108:111], v[156:159], v[188:191], v[108:111]
	v_mfma_f32_16x16x32_bf16 v[128:131], v[152:155], v[176:179], v[128:131]
	v_mfma_f32_16x16x32_bf16 v[128:131], v[156:159], v[180:183], v[128:131]
	s_setprio 0
	s_setprio 1
	v_mfma_f32_16x16x32_bf16 v[120:123], v[160:163], v[176:179], v[120:123]
	v_mfma_f32_16x16x32_bf16 v[120:123], v[164:167], v[180:183], v[120:123]
	v_mfma_f32_16x16x32_bf16 v[104:107], v[160:163], v[184:187], v[104:107]
	v_mfma_f32_16x16x32_bf16 v[104:107], v[164:167], v[188:191], v[104:107]
	v_mfma_f32_16x16x32_bf16 v[88:91], v[160:163], v[192:195], v[88:91]
	v_mfma_f32_16x16x32_bf16 v[88:91], v[164:167], v[196:199], v[88:91]
	v_mfma_f32_16x16x32_bf16 v[72:75], v[160:163], v[200:203], v[72:75]
	v_mfma_f32_16x16x32_bf16 v[72:75], v[164:167], v[204:207], v[72:75]
	v_mfma_f32_16x16x32_bf16 v[68:71], v[168:171], v[200:203], v[68:71]
	v_mfma_f32_16x16x32_bf16 v[68:71], v[172:175], v[204:207], v[68:71]
	v_mfma_f32_16x16x32_bf16 v[84:87], v[168:171], v[192:195], v[84:87]
	v_mfma_f32_16x16x32_bf16 v[84:87], v[172:175], v[196:199], v[84:87]
	v_mfma_f32_16x16x32_bf16 v[100:103], v[168:171], v[184:187], v[100:103]
	v_mfma_f32_16x16x32_bf16 v[100:103], v[172:175], v[188:191], v[100:103]
	v_mfma_f32_16x16x32_bf16 v[116:119], v[168:171], v[176:179], v[116:119]
	v_mfma_f32_16x16x32_bf16 v[116:119], v[172:175], v[180:183], v[116:119]
	s_setprio 0
	s_barrier
	s_mov_b32 m0, s26
	v_lshl_add_u64 v[208:209], v[208:209], 0, s[64:65]
	ds_read_b128 v[176:179], v143 offset:49152
	ds_read_b128 v[180:183], v143 offset:50176
	ds_read_b128 v[184:187], v143 offset:51200
	ds_read_b128 v[188:191], v143 offset:52224
	ds_read_b128 v[192:195], v143 offset:53248
	ds_read_b128 v[196:199], v143 offset:54272
	ds_read_b128 v[200:203], v143 offset:55296
	ds_read_b128 v[204:207], v143 offset:56320
	global_load_lds_dwordx4 v[208:209], off
	v_lshl_add_u64 v[208:209], v[210:211], 0, s[64:65]
	s_mov_b32 m0, s27
	s_nop 0
	global_load_lds_dwordx4 v[208:209], off
	v_lshl_add_u64 v[208:209], v[216:217], 0, s[64:65]
	s_mov_b32 m0, s37
	s_nop 0
	global_load_lds_dwordx4 v[208:209], off
	v_lshl_add_u64 v[208:209], v[218:219], 0, s[64:65]
	s_mov_b32 m0, s40
	s_nop 0
	global_load_lds_dwordx4 v[208:209], off
	v_lshl_add_u64 v[208:209], v[220:221], 0, s[64:65]
	s_mov_b32 m0, s34
	s_nop 0
	global_load_lds_dwordx4 v[208:209], off
	v_lshl_add_u64 v[208:209], v[222:223], 0, s[64:65]
	s_mov_b32 m0, s35
	s_nop 0
	global_load_lds_dwordx4 v[208:209], off
	s_waitcnt vmcnt(8)
	s_waitcnt lgkmcnt(0)
	s_barrier
	s_setprio 1
	s_waitcnt lgkmcnt(0)
	v_mfma_f32_16x16x32_bf16 v[64:67], v[144:147], v[176:179], v[64:67]
	v_mfma_f32_16x16x32_bf16 v[64:67], v[148:151], v[180:183], v[64:67]
	v_mfma_f32_16x16x32_bf16 v[48:51], v[144:147], v[184:187], v[48:51]
	v_mfma_f32_16x16x32_bf16 v[48:51], v[148:151], v[188:191], v[48:51]
	v_mfma_f32_16x16x32_bf16 v[32:35], v[144:147], v[192:195], v[32:35]
	v_mfma_f32_16x16x32_bf16 v[32:35], v[148:151], v[196:199], v[32:35]
	v_mfma_f32_16x16x32_bf16 v[16:19], v[144:147], v[200:203], v[16:19]
	v_mfma_f32_16x16x32_bf16 v[16:19], v[148:151], v[204:207], v[16:19]
	v_mfma_f32_16x16x32_bf16 v[12:15], v[152:155], v[200:203], v[12:15]
	v_mfma_f32_16x16x32_bf16 v[12:15], v[156:159], v[204:207], v[12:15]
	v_mfma_f32_16x16x32_bf16 v[28:31], v[152:155], v[192:195], v[28:31]
	v_mfma_f32_16x16x32_bf16 v[28:31], v[156:159], v[196:199], v[28:31]
	v_mfma_f32_16x16x32_bf16 v[44:47], v[152:155], v[184:187], v[44:47]
	v_mfma_f32_16x16x32_bf16 v[44:47], v[156:159], v[188:191], v[44:47]
	v_mfma_f32_16x16x32_bf16 v[60:63], v[152:155], v[176:179], v[60:63]
	v_mfma_f32_16x16x32_bf16 v[60:63], v[156:159], v[180:183], v[60:63]
	s_setprio 0
	s_setprio 1
	v_mfma_f32_16x16x32_bf16 v[56:59], v[160:163], v[176:179], v[56:59]
	v_mfma_f32_16x16x32_bf16 v[56:59], v[164:167], v[180:183], v[56:59]
	v_mfma_f32_16x16x32_bf16 v[40:43], v[160:163], v[184:187], v[40:43]
	v_mfma_f32_16x16x32_bf16 v[40:43], v[164:167], v[188:191], v[40:43]
	v_mfma_f32_16x16x32_bf16 v[24:27], v[160:163], v[192:195], v[24:27]
	v_mfma_f32_16x16x32_bf16 v[24:27], v[164:167], v[196:199], v[24:27]
	v_mfma_f32_16x16x32_bf16 v[8:11], v[160:163], v[200:203], v[8:11]
	v_mfma_f32_16x16x32_bf16 v[8:11], v[164:167], v[204:207], v[8:11]
	v_mfma_f32_16x16x32_bf16 v[4:7], v[168:171], v[200:203], v[4:7]
	v_mfma_f32_16x16x32_bf16 v[4:7], v[172:175], v[204:207], v[4:7]
	v_mfma_f32_16x16x32_bf16 v[20:23], v[168:171], v[192:195], v[20:23]
	v_mfma_f32_16x16x32_bf16 v[20:23], v[172:175], v[196:199], v[20:23]
	v_mfma_f32_16x16x32_bf16 v[36:39], v[168:171], v[184:187], v[36:39]
	v_mfma_f32_16x16x32_bf16 v[36:39], v[172:175], v[188:191], v[36:39]
	v_mfma_f32_16x16x32_bf16 v[52:55], v[168:171], v[176:179], v[52:55]
	v_mfma_f32_16x16x32_bf16 v[52:55], v[172:175], v[180:183], v[52:55]
	s_setprio 0
	s_barrier
	s_cmp_ge_i32 s43, s41
	s_mov_b64 s[8:9], s[10:11]
	s_mov_b32 s12, s43
	s_cbranch_scc0 .LBB0_2329

.LBB0_2896:
	v_add_u32_e32 v148, s18, v126
	v_add_u32_e32 v172, s19, v126
	s_add_u32 s12, s46, s8
	ds_read_b128 v[128:131], v148
	ds_read_b128 v[132:135], v148 offset:1024
	ds_read_b128 v[140:143], v148 offset:2048
	ds_read_b128 v[148:151], v148 offset:3072
	ds_read_b128 v[160:163], v172
	ds_read_b128 v[164:167], v172 offset:1024
	ds_read_b128 v[168:171], v172 offset:2048
	ds_read_b128 v[172:175], v172 offset:3072
	s_addc_u32 s13, s47, s9
	s_add_u32 s12, s12, 0x34400100
	s_addc_u32 s13, s13, 0
	s_add_u32 s16, s48, s8
	s_addc_u32 s51, s49, s9
	s_cmpk_eq_i32 s8, 0xf00
	s_cselect_b32 s15, s11, s13
	s_cselect_b32 s14, s10, s12
	s_cselect_b32 s13, s3, s51
	s_cselect_b32 s12, s2, s16
	v_lshl_add_u64 v[208:209], v[122:123], 0, s[8:9]
	s_add_i32 m0, s27, 0xc000
	ds_read_b128 v[176:179], v127
	ds_read_b128 v[180:183], v127 offset:1024
	ds_read_b128 v[184:187], v127 offset:2048
	ds_read_b128 v[188:191], v127 offset:3072
	ds_read_b128 v[192:195], v127 offset:4096
	ds_read_b128 v[196:199], v127 offset:5120
	ds_read_b128 v[200:203], v127 offset:6144
	ds_read_b128 v[204:207], v127 offset:7168
	global_load_lds_dwordx4 v[208:209], off
	v_lshl_add_u64 v[208:209], v[124:125], 0, s[8:9]
	s_add_i32 m0, s27, 0xe000
	s_nop 0
	global_load_lds_dwordx4 v[208:209], off
	s_waitcnt vmcnt(8)
	s_waitcnt lgkmcnt(0)
	s_barrier
	s_setprio 1
	s_waitcnt lgkmcnt(0)
	v_mfma_f32_16x16x32_bf16 v[156:159], v[128:131], v[176:179], v[156:159]
	v_mfma_f32_16x16x32_bf16 v[156:159], v[132:135], v[180:183], v[156:159]
	v_mfma_f32_16x16x32_bf16 v[112:115], v[128:131], v[184:187], v[112:115]
	v_mfma_f32_16x16x32_bf16 v[112:115], v[132:135], v[188:191], v[112:115]
	v_mfma_f32_16x16x32_bf16 v[96:99], v[128:131], v[192:195], v[96:99]
	v_mfma_f32_16x16x32_bf16 v[96:99], v[132:135], v[196:199], v[96:99]
	v_mfma_f32_16x16x32_bf16 v[80:83], v[128:131], v[200:203], v[80:83]
	v_mfma_f32_16x16x32_bf16 v[80:83], v[132:135], v[204:207], v[80:83]
	v_mfma_f32_16x16x32_bf16 v[76:79], v[140:143], v[200:203], v[76:79]
	v_mfma_f32_16x16x32_bf16 v[76:79], v[148:151], v[204:207], v[76:79]
	v_mfma_f32_16x16x32_bf16 v[92:95], v[140:143], v[192:195], v[92:95]
	v_mfma_f32_16x16x32_bf16 v[92:95], v[148:151], v[196:199], v[92:95]
	v_mfma_f32_16x16x32_bf16 v[108:111], v[140:143], v[184:187], v[108:111]
	v_mfma_f32_16x16x32_bf16 v[108:111], v[148:151], v[188:191], v[108:111]
	v_mfma_f32_16x16x32_bf16 v[152:155], v[140:143], v[176:179], v[152:155]
	v_mfma_f32_16x16x32_bf16 v[152:155], v[148:151], v[180:183], v[152:155]
	s_setprio 0
	s_setprio 1
	v_mfma_f32_16x16x32_bf16 v[144:147], v[160:163], v[176:179], v[144:147]
	v_mfma_f32_16x16x32_bf16 v[144:147], v[164:167], v[180:183], v[144:147]
	v_mfma_f32_16x16x32_bf16 v[104:107], v[160:163], v[184:187], v[104:107]
	v_mfma_f32_16x16x32_bf16 v[104:107], v[164:167], v[188:191], v[104:107]
	v_mfma_f32_16x16x32_bf16 v[88:91], v[160:163], v[192:195], v[88:91]
	v_mfma_f32_16x16x32_bf16 v[88:91], v[164:167], v[196:199], v[88:91]
	v_mfma_f32_16x16x32_bf16 v[72:75], v[160:163], v[200:203], v[72:75]
	v_mfma_f32_16x16x32_bf16 v[72:75], v[164:167], v[204:207], v[72:75]
	v_mfma_f32_16x16x32_bf16 v[68:71], v[168:171], v[200:203], v[68:71]
	v_mfma_f32_16x16x32_bf16 v[68:71], v[172:175], v[204:207], v[68:71]
	v_mfma_f32_16x16x32_bf16 v[84:87], v[168:171], v[192:195], v[84:87]
	v_mfma_f32_16x16x32_bf16 v[84:87], v[172:175], v[196:199], v[84:87]
	v_mfma_f32_16x16x32_bf16 v[100:103], v[168:171], v[184:187], v[100:103]
	v_mfma_f32_16x16x32_bf16 v[100:103], v[172:175], v[188:191], v[100:103]
	v_mfma_f32_16x16x32_bf16 v[136:139], v[168:171], v[176:179], v[136:139]
	v_mfma_f32_16x16x32_bf16 v[136:139], v[172:175], v[180:183], v[136:139]
	s_setprio 0
	s_barrier
	s_mov_b32 m0, s23
	v_lshl_add_u64 v[208:209], s[12:13], 0, v[2:3]
	s_add_u32 s52, s12, 0x80000
	ds_read_b128 v[176:179], v127 offset:16384
	ds_read_b128 v[180:183], v127 offset:17408
	ds_read_b128 v[184:187], v127 offset:18432
	ds_read_b128 v[188:191], v127 offset:19456
	ds_read_b128 v[192:195], v127 offset:20480
	ds_read_b128 v[196:199], v127 offset:21504
	ds_read_b128 v[200:203], v127 offset:22528
	ds_read_b128 v[204:207], v127 offset:23552
	global_load_lds_dwordx4 v[208:209], off
	v_lshl_add_u64 v[210:211], s[12:13], 0, v[120:121]
	s_mov_b32 m0, s24
	s_addc_u32 s53, s13, 0
	global_load_lds_dwordx4 v[210:211], off
	v_lshl_add_u64 v[216:217], s[52:53], 0, v[2:3]
	s_mov_b32 m0, s25
	v_lshl_add_u64 v[218:219], s[14:15], 0, v[118:119]
	global_load_lds_dwordx4 v[216:217], off
	v_lshl_add_u64 v[216:217], s[52:53], 0, v[120:121]
	s_mov_b32 m0, s26
	s_nop 0
	global_load_lds_dwordx4 v[216:217], off
	v_lshl_add_u64 v[216:217], s[14:15], 0, v[116:117]
	s_mov_b32 m0, s27
	s_nop 0
	global_load_lds_dwordx4 v[216:217], off
	s_mov_b32 m0, s35
	s_nop 0
	global_load_lds_dwordx4 v[218:219], off
	s_waitcnt vmcnt(8)
	s_waitcnt lgkmcnt(0)
	s_barrier
	s_setprio 1
	s_waitcnt lgkmcnt(0)
	v_mfma_f32_16x16x32_bf16 v[64:67], v[128:131], v[176:179], v[64:67]
	v_mfma_f32_16x16x32_bf16 v[64:67], v[132:135], v[180:183], v[64:67]
	v_mfma_f32_16x16x32_bf16 v[48:51], v[128:131], v[184:187], v[48:51]
	v_mfma_f32_16x16x32_bf16 v[48:51], v[132:135], v[188:191], v[48:51]
	v_mfma_f32_16x16x32_bf16 v[32:35], v[128:131], v[192:195], v[32:35]
	v_mfma_f32_16x16x32_bf16 v[32:35], v[132:135], v[196:199], v[32:35]
	v_mfma_f32_16x16x32_bf16 v[16:19], v[128:131], v[200:203], v[16:19]
	v_mfma_f32_16x16x32_bf16 v[16:19], v[132:135], v[204:207], v[16:19]
	v_mfma_f32_16x16x32_bf16 v[12:15], v[140:143], v[200:203], v[12:15]
	v_mfma_f32_16x16x32_bf16 v[12:15], v[148:151], v[204:207], v[12:15]
	v_mfma_f32_16x16x32_bf16 v[28:31], v[140:143], v[192:195], v[28:31]
	v_mfma_f32_16x16x32_bf16 v[28:31], v[148:151], v[196:199], v[28:31]
	v_mfma_f32_16x16x32_bf16 v[44:47], v[140:143], v[184:187], v[44:47]
	v_mfma_f32_16x16x32_bf16 v[44:47], v[148:151], v[188:191], v[44:47]
	v_mfma_f32_16x16x32_bf16 v[60:63], v[140:143], v[176:179], v[60:63]
	v_mfma_f32_16x16x32_bf16 v[60:63], v[148:151], v[180:183], v[60:63]
	s_setprio 0
	s_setprio 1
	v_mfma_f32_16x16x32_bf16 v[56:59], v[160:163], v[176:179], v[56:59]
	v_mfma_f32_16x16x32_bf16 v[56:59], v[164:167], v[180:183], v[56:59]
	v_mfma_f32_16x16x32_bf16 v[40:43], v[160:163], v[184:187], v[40:43]
	v_mfma_f32_16x16x32_bf16 v[40:43], v[164:167], v[188:191], v[40:43]
	v_mfma_f32_16x16x32_bf16 v[24:27], v[160:163], v[192:195], v[24:27]
	v_mfma_f32_16x16x32_bf16 v[24:27], v[164:167], v[196:199], v[24:27]
	v_mfma_f32_16x16x32_bf16 v[8:11], v[160:163], v[200:203], v[8:11]
	v_mfma_f32_16x16x32_bf16 v[8:11], v[164:167], v[204:207], v[8:11]
	v_mfma_f32_16x16x32_bf16 v[4:7], v[168:171], v[200:203], v[4:7]
	v_mfma_f32_16x16x32_bf16 v[4:7], v[172:175], v[204:207], v[4:7]
	v_mfma_f32_16x16x32_bf16 v[20:23], v[168:171], v[192:195], v[20:23]
	v_mfma_f32_16x16x32_bf16 v[20:23], v[172:175], v[196:199], v[20:23]
	v_mfma_f32_16x16x32_bf16 v[36:39], v[168:171], v[184:187], v[36:39]
	v_mfma_f32_16x16x32_bf16 v[36:39], v[172:175], v[188:191], v[36:39]
	v_mfma_f32_16x16x32_bf16 v[52:55], v[168:171], v[176:179], v[52:55]
	v_mfma_f32_16x16x32_bf16 v[52:55], v[172:175], v[180:183], v[52:55]
	s_setprio 0
	s_barrier
	v_add_u32_e32 v148, s20, v126
	v_add_u32_e32 v172, s21, v126
	ds_read_b128 v[128:131], v148
	ds_read_b128 v[132:135], v148 offset:1024
	ds_read_b128 v[140:143], v148 offset:2048
	ds_read_b128 v[148:151], v148 offset:3072
	ds_read_b128 v[160:163], v172
	ds_read_b128 v[164:167], v172 offset:1024
	ds_read_b128 v[168:171], v172 offset:2048
	ds_read_b128 v[172:175], v172 offset:3072
	s_add_u32 s14, s14, 0x80000
	s_addc_u32 s15, s15, 0
	s_mov_b32 m0, s37
	v_lshl_add_u64 v[220:221], s[14:15], 0, v[116:117]
	ds_read_b128 v[176:179], v127 offset:32768
	ds_read_b128 v[180:183], v127 offset:33792
	ds_read_b128 v[184:187], v127 offset:34816
	ds_read_b128 v[188:191], v127 offset:35840
	ds_read_b128 v[192:195], v127 offset:36864
	ds_read_b128 v[196:199], v127 offset:37888
	ds_read_b128 v[200:203], v127 offset:38912
	ds_read_b128 v[204:207], v127 offset:39936
	global_load_lds_dwordx4 v[220:221], off
	v_lshl_add_u64 v[220:221], s[14:15], 0, v[118:119]
	s_mov_b32 m0, s38
	s_nop 0
	global_load_lds_dwordx4 v[220:221], off
	s_waitcnt vmcnt(8)
	s_waitcnt lgkmcnt(0)
	s_barrier
	s_setprio 1
	s_waitcnt lgkmcnt(0)
	v_mfma_f32_16x16x32_bf16 v[156:159], v[128:131], v[176:179], v[156:159]
	v_mfma_f32_16x16x32_bf16 v[156:159], v[132:135], v[180:183], v[156:159]
	v_mfma_f32_16x16x32_bf16 v[112:115], v[128:131], v[184:187], v[112:115]
	v_mfma_f32_16x16x32_bf16 v[112:115], v[132:135], v[188:191], v[112:115]
	v_mfma_f32_16x16x32_bf16 v[96:99], v[128:131], v[192:195], v[96:99]
	v_mfma_f32_16x16x32_bf16 v[96:99], v[132:135], v[196:199], v[96:99]
	v_mfma_f32_16x16x32_bf16 v[80:83], v[128:131], v[200:203], v[80:83]
	v_mfma_f32_16x16x32_bf16 v[80:83], v[132:135], v[204:207], v[80:83]
	v_mfma_f32_16x16x32_bf16 v[76:79], v[140:143], v[200:203], v[76:79]
	v_mfma_f32_16x16x32_bf16 v[76:79], v[148:151], v[204:207], v[76:79]
	v_mfma_f32_16x16x32_bf16 v[92:95], v[140:143], v[192:195], v[92:95]
	v_mfma_f32_16x16x32_bf16 v[92:95], v[148:151], v[196:199], v[92:95]
	v_mfma_f32_16x16x32_bf16 v[108:111], v[140:143], v[184:187], v[108:111]
	v_mfma_f32_16x16x32_bf16 v[108:111], v[148:151], v[188:191], v[108:111]
	v_mfma_f32_16x16x32_bf16 v[152:155], v[140:143], v[176:179], v[152:155]
	v_mfma_f32_16x16x32_bf16 v[152:155], v[148:151], v[180:183], v[152:155]
	s_setprio 0
	s_setprio 1
	v_mfma_f32_16x16x32_bf16 v[144:147], v[160:163], v[176:179], v[144:147]
	v_mfma_f32_16x16x32_bf16 v[144:147], v[164:167], v[180:183], v[144:147]
	v_mfma_f32_16x16x32_bf16 v[104:107], v[160:163], v[184:187], v[104:107]
	v_mfma_f32_16x16x32_bf16 v[104:107], v[164:167], v[188:191], v[104:107]
	v_mfma_f32_16x16x32_bf16 v[88:91], v[160:163], v[192:195], v[88:91]
	v_mfma_f32_16x16x32_bf16 v[88:91], v[164:167], v[196:199], v[88:91]
	v_mfma_f32_16x16x32_bf16 v[72:75], v[160:163], v[200:203], v[72:75]
	v_mfma_f32_16x16x32_bf16 v[72:75], v[164:167], v[204:207], v[72:75]
	v_mfma_f32_16x16x32_bf16 v[68:71], v[168:171], v[200:203], v[68:71]
	v_mfma_f32_16x16x32_bf16 v[68:71], v[172:175], v[204:207], v[68:71]
	v_mfma_f32_16x16x32_bf16 v[84:87], v[168:171], v[192:195], v[84:87]
	v_mfma_f32_16x16x32_bf16 v[84:87], v[172:175], v[196:199], v[84:87]
	v_mfma_f32_16x16x32_bf16 v[100:103], v[168:171], v[184:187], v[100:103]
	v_mfma_f32_16x16x32_bf16 v[100:103], v[172:175], v[188:191], v[100:103]
	v_mfma_f32_16x16x32_bf16 v[136:139], v[168:171], v[176:179], v[136:139]
	v_mfma_f32_16x16x32_bf16 v[136:139], v[172:175], v[180:183], v[136:139]
	s_setprio 0
	s_barrier
	s_mov_b32 m0, s40
	v_lshl_add_u64 v[208:209], v[208:209], 0, s[64:65]
	s_add_u32 s12, s12, 0x80080
	ds_read_b128 v[176:179], v127 offset:49152
	ds_read_b128 v[180:183], v127 offset:50176
	ds_read_b128 v[184:187], v127 offset:51200
	ds_read_b128 v[188:191], v127 offset:52224
	ds_read_b128 v[192:195], v127 offset:53248
	ds_read_b128 v[196:199], v127 offset:54272
	ds_read_b128 v[200:203], v127 offset:55296
	ds_read_b128 v[204:207], v127 offset:56320
	global_load_lds_dwordx4 v[208:209], off
	v_lshl_add_u64 v[208:209], v[210:211], 0, s[64:65]
	s_mov_b32 m0, s41
	s_addc_u32 s13, s13, 0
	global_load_lds_dwordx4 v[208:209], off
	v_lshl_add_u64 v[208:209], s[12:13], 0, v[2:3]
	s_mov_b32 m0, s44
	s_nop 0
	global_load_lds_dwordx4 v[208:209], off
	v_lshl_add_u64 v[208:209], s[12:13], 0, v[120:121]
	s_mov_b32 m0, s45
	s_nop 0
	global_load_lds_dwordx4 v[208:209], off
	v_lshl_add_u64 v[208:209], v[216:217], 0, s[64:65]
	s_mov_b32 m0, s42
	s_nop 0
	global_load_lds_dwordx4 v[208:209], off
	v_lshl_add_u64 v[208:209], v[218:219], 0, s[64:65]
	s_mov_b32 m0, s43
	s_nop 0
	global_load_lds_dwordx4 v[208:209], off
	s_waitcnt vmcnt(8)
	s_waitcnt lgkmcnt(0)
	s_barrier
	s_setprio 1
	s_waitcnt lgkmcnt(0)
	v_mfma_f32_16x16x32_bf16 v[64:67], v[128:131], v[176:179], v[64:67]
	v_mfma_f32_16x16x32_bf16 v[64:67], v[132:135], v[180:183], v[64:67]
	v_mfma_f32_16x16x32_bf16 v[48:51], v[128:131], v[184:187], v[48:51]
	v_mfma_f32_16x16x32_bf16 v[48:51], v[132:135], v[188:191], v[48:51]
	v_mfma_f32_16x16x32_bf16 v[32:35], v[128:131], v[192:195], v[32:35]
	v_mfma_f32_16x16x32_bf16 v[32:35], v[132:135], v[196:199], v[32:35]
	v_mfma_f32_16x16x32_bf16 v[16:19], v[128:131], v[200:203], v[16:19]
	v_mfma_f32_16x16x32_bf16 v[16:19], v[132:135], v[204:207], v[16:19]
	v_mfma_f32_16x16x32_bf16 v[12:15], v[140:143], v[200:203], v[12:15]
	v_mfma_f32_16x16x32_bf16 v[12:15], v[148:151], v[204:207], v[12:15]
	v_mfma_f32_16x16x32_bf16 v[28:31], v[140:143], v[192:195], v[28:31]
	v_mfma_f32_16x16x32_bf16 v[28:31], v[148:151], v[196:199], v[28:31]
	v_mfma_f32_16x16x32_bf16 v[44:47], v[140:143], v[184:187], v[44:47]
	v_mfma_f32_16x16x32_bf16 v[44:47], v[148:151], v[188:191], v[44:47]
	v_mfma_f32_16x16x32_bf16 v[60:63], v[140:143], v[176:179], v[60:63]
	v_mfma_f32_16x16x32_bf16 v[60:63], v[148:151], v[180:183], v[60:63]
	s_setprio 0
	s_setprio 1
	v_mfma_f32_16x16x32_bf16 v[56:59], v[160:163], v[176:179], v[56:59]
	v_mfma_f32_16x16x32_bf16 v[56:59], v[164:167], v[180:183], v[56:59]
	v_mfma_f32_16x16x32_bf16 v[40:43], v[160:163], v[184:187], v[40:43]
	v_mfma_f32_16x16x32_bf16 v[40:43], v[164:167], v[188:191], v[40:43]
	v_mfma_f32_16x16x32_bf16 v[24:27], v[160:163], v[192:195], v[24:27]
	v_mfma_f32_16x16x32_bf16 v[24:27], v[164:167], v[196:199], v[24:27]
	v_mfma_f32_16x16x32_bf16 v[8:11], v[160:163], v[200:203], v[8:11]
	v_mfma_f32_16x16x32_bf16 v[8:11], v[164:167], v[204:207], v[8:11]
	v_mfma_f32_16x16x32_bf16 v[4:7], v[168:171], v[200:203], v[4:7]
	v_mfma_f32_16x16x32_bf16 v[4:7], v[172:175], v[204:207], v[4:7]
	v_mfma_f32_16x16x32_bf16 v[20:23], v[168:171], v[192:195], v[20:23]
	v_mfma_f32_16x16x32_bf16 v[20:23], v[172:175], v[196:199], v[20:23]
	v_mfma_f32_16x16x32_bf16 v[36:39], v[168:171], v[184:187], v[36:39]
	v_mfma_f32_16x16x32_bf16 v[36:39], v[172:175], v[188:191], v[36:39]
	v_mfma_f32_16x16x32_bf16 v[52:55], v[168:171], v[176:179], v[52:55]
	v_mfma_f32_16x16x32_bf16 v[52:55], v[172:175], v[180:183], v[52:55]
	s_setprio 0
	s_barrier
	s_add_i32 s50, s50, 2
	s_add_u32 s8, s8, 0x100
	s_addc_u32 s9, s9, 0
	s_cmp_gt_u32 s50, 29
	s_cbranch_scc0 .LBB0_2896
	s_cmpk_lt_u32 s22, 0x100
	s_cbranch_scc0 .LBB0_2899
	s_barrier

.LBB0_3116:
	v_add_u32_e32 v142, s26, v144
	ds_read_b128 v[146:149], v142
	ds_read_b128 v[150:153], v142 offset:1024
	ds_read_b128 v[154:157], v142 offset:2048
	ds_read_b128 v[158:161], v142 offset:3072
	v_add_u32_e32 v142, s40, v144
	ds_read_b128 v[162:165], v142
	ds_read_b128 v[166:169], v142 offset:1024
	ds_read_b128 v[170:173], v142 offset:2048
	ds_read_b128 v[174:177], v142 offset:3072
	s_add_u32 s18, s34, 0xfff80080
	s_addc_u32 s19, s35, -1
	s_cmp_eq_u32 s74, 28
	s_cselect_b32 s39, s13, s19
	s_cselect_b32 s38, s69, s18
	s_cselect_b32 s19, s11, s73
	s_cselect_b32 s18, s70, s71
	v_lshl_add_u64 v[142:143], s[34:35], 0, v[138:139]
	s_add_i32 m0, s43, 0xc000
	ds_read_b128 v[178:181], v145
	ds_read_b128 v[182:185], v145 offset:1024
	ds_read_b128 v[186:189], v145 offset:2048
	ds_read_b128 v[190:193], v145 offset:3072
	ds_read_b128 v[194:197], v145 offset:4096
	ds_read_b128 v[198:201], v145 offset:5120
	ds_read_b128 v[202:205], v145 offset:6144
	ds_read_b128 v[206:209], v145 offset:7168
	global_load_lds_dwordx4 v[142:143], off
	v_lshl_add_u64 v[142:143], s[34:35], 0, v[140:141]
	s_add_i32 m0, s43, 0xe000
	s_nop 0
	global_load_lds_dwordx4 v[142:143], off
	s_waitcnt vmcnt(8)
	s_waitcnt lgkmcnt(0)
	s_barrier
	s_setprio 1
	s_waitcnt lgkmcnt(0)
	v_mfma_f32_16x16x32_bf16 v[128:131], v[146:149], v[178:181], v[128:131]
	v_mfma_f32_16x16x32_bf16 v[128:131], v[150:153], v[182:185], v[128:131]
	v_mfma_f32_16x16x32_bf16 v[112:115], v[146:149], v[186:189], v[112:115]
	v_mfma_f32_16x16x32_bf16 v[112:115], v[150:153], v[190:193], v[112:115]
	v_mfma_f32_16x16x32_bf16 v[96:99], v[146:149], v[194:197], v[96:99]
	v_mfma_f32_16x16x32_bf16 v[96:99], v[150:153], v[198:201], v[96:99]
	v_mfma_f32_16x16x32_bf16 v[80:83], v[146:149], v[202:205], v[80:83]
	v_mfma_f32_16x16x32_bf16 v[80:83], v[150:153], v[206:209], v[80:83]
	v_mfma_f32_16x16x32_bf16 v[72:75], v[154:157], v[202:205], v[72:75]
	v_mfma_f32_16x16x32_bf16 v[72:75], v[158:161], v[206:209], v[72:75]
	v_mfma_f32_16x16x32_bf16 v[88:91], v[154:157], v[194:197], v[88:91]
	v_mfma_f32_16x16x32_bf16 v[88:91], v[158:161], v[198:201], v[88:91]
	v_mfma_f32_16x16x32_bf16 v[104:107], v[154:157], v[186:189], v[104:107]
	v_mfma_f32_16x16x32_bf16 v[104:107], v[158:161], v[190:193], v[104:107]
	v_mfma_f32_16x16x32_bf16 v[120:123], v[154:157], v[178:181], v[120:123]
	v_mfma_f32_16x16x32_bf16 v[120:123], v[158:161], v[182:185], v[120:123]
	s_setprio 0
	s_setprio 1
	v_mfma_f32_16x16x32_bf16 v[124:127], v[162:165], v[178:181], v[124:127]
	v_mfma_f32_16x16x32_bf16 v[124:127], v[166:169], v[182:185], v[124:127]
	v_mfma_f32_16x16x32_bf16 v[108:111], v[162:165], v[186:189], v[108:111]
	v_mfma_f32_16x16x32_bf16 v[108:111], v[166:169], v[190:193], v[108:111]
	v_mfma_f32_16x16x32_bf16 v[92:95], v[162:165], v[194:197], v[92:95]
	v_mfma_f32_16x16x32_bf16 v[92:95], v[166:169], v[198:201], v[92:95]
	v_mfma_f32_16x16x32_bf16 v[76:79], v[162:165], v[202:205], v[76:79]
	v_mfma_f32_16x16x32_bf16 v[76:79], v[166:169], v[206:209], v[76:79]
	v_mfma_f32_16x16x32_bf16 v[68:71], v[170:173], v[202:205], v[68:71]
	v_mfma_f32_16x16x32_bf16 v[68:71], v[174:177], v[206:209], v[68:71]
	v_mfma_f32_16x16x32_bf16 v[84:87], v[170:173], v[194:197], v[84:87]
	v_mfma_f32_16x16x32_bf16 v[84:87], v[174:177], v[198:201], v[84:87]
	v_mfma_f32_16x16x32_bf16 v[100:103], v[170:173], v[186:189], v[100:103]
	v_mfma_f32_16x16x32_bf16 v[100:103], v[174:177], v[190:193], v[100:103]
	v_mfma_f32_16x16x32_bf16 v[116:119], v[170:173], v[178:181], v[116:119]
	v_mfma_f32_16x16x32_bf16 v[116:119], v[174:177], v[182:185], v[116:119]
	s_setprio 0
	s_barrier
	s_mov_b32 m0, s27
	v_lshl_add_u64 v[142:143], s[18:19], 0, v[2:3]
	s_add_u32 s76, s18, 0x80000
	ds_read_b128 v[178:181], v145 offset:16384
	ds_read_b128 v[182:185], v145 offset:17408
	ds_read_b128 v[186:189], v145 offset:18432
	ds_read_b128 v[190:193], v145 offset:19456
	ds_read_b128 v[194:197], v145 offset:20480
	ds_read_b128 v[198:201], v145 offset:21504
	ds_read_b128 v[202:205], v145 offset:22528
	ds_read_b128 v[206:209], v145 offset:23552
	global_load_lds_dwordx4 v[142:143], off
	v_lshl_add_u64 v[210:211], s[18:19], 0, v[132:133]
	s_mov_b32 m0, s37
	s_addc_u32 s77, s19, 0
	global_load_lds_dwordx4 v[210:211], off
	v_lshl_add_u64 v[212:213], s[76:77], 0, v[2:3]
	s_mov_b32 m0, s41
	v_lshl_add_u64 v[214:215], s[38:39], 0, v[134:135]
	global_load_lds_dwordx4 v[212:213], off
	v_lshl_add_u64 v[212:213], s[76:77], 0, v[132:133]
	s_mov_b32 m0, s42
	s_nop 0
	global_load_lds_dwordx4 v[212:213], off
	v_lshl_add_u64 v[212:213], s[38:39], 0, v[136:137]
	s_mov_b32 m0, s43
	s_nop 0
	global_load_lds_dwordx4 v[212:213], off
	s_mov_b32 m0, s44
	s_nop 0
	global_load_lds_dwordx4 v[214:215], off
	s_waitcnt vmcnt(8)
	s_waitcnt lgkmcnt(0)
	s_barrier
	s_setprio 1
	s_waitcnt lgkmcnt(0)
	v_mfma_f32_16x16x32_bf16 v[64:67], v[146:149], v[178:181], v[64:67]
	v_mfma_f32_16x16x32_bf16 v[64:67], v[150:153], v[182:185], v[64:67]
	v_mfma_f32_16x16x32_bf16 v[48:51], v[146:149], v[186:189], v[48:51]
	v_mfma_f32_16x16x32_bf16 v[48:51], v[150:153], v[190:193], v[48:51]
	v_mfma_f32_16x16x32_bf16 v[32:35], v[146:149], v[194:197], v[32:35]
	v_mfma_f32_16x16x32_bf16 v[32:35], v[150:153], v[198:201], v[32:35]
	v_mfma_f32_16x16x32_bf16 v[16:19], v[146:149], v[202:205], v[16:19]
	v_mfma_f32_16x16x32_bf16 v[16:19], v[150:153], v[206:209], v[16:19]
	v_mfma_f32_16x16x32_bf16 v[8:11], v[154:157], v[202:205], v[8:11]
	v_mfma_f32_16x16x32_bf16 v[8:11], v[158:161], v[206:209], v[8:11]
	v_mfma_f32_16x16x32_bf16 v[24:27], v[154:157], v[194:197], v[24:27]
	v_mfma_f32_16x16x32_bf16 v[24:27], v[158:161], v[198:201], v[24:27]
	v_mfma_f32_16x16x32_bf16 v[40:43], v[154:157], v[186:189], v[40:43]
	v_mfma_f32_16x16x32_bf16 v[40:43], v[158:161], v[190:193], v[40:43]
	v_mfma_f32_16x16x32_bf16 v[56:59], v[154:157], v[178:181], v[56:59]
	v_mfma_f32_16x16x32_bf16 v[56:59], v[158:161], v[182:185], v[56:59]
	s_setprio 0
	s_setprio 1
	v_mfma_f32_16x16x32_bf16 v[60:63], v[162:165], v[178:181], v[60:63]
	v_mfma_f32_16x16x32_bf16 v[60:63], v[166:169], v[182:185], v[60:63]
	v_mfma_f32_16x16x32_bf16 v[44:47], v[162:165], v[186:189], v[44:47]
	v_mfma_f32_16x16x32_bf16 v[44:47], v[166:169], v[190:193], v[44:47]
	v_mfma_f32_16x16x32_bf16 v[28:31], v[162:165], v[194:197], v[28:31]
	v_mfma_f32_16x16x32_bf16 v[28:31], v[166:169], v[198:201], v[28:31]
	v_mfma_f32_16x16x32_bf16 v[12:15], v[162:165], v[202:205], v[12:15]
	v_mfma_f32_16x16x32_bf16 v[12:15], v[166:169], v[206:209], v[12:15]
	v_mfma_f32_16x16x32_bf16 v[4:7], v[170:173], v[202:205], v[4:7]
	v_mfma_f32_16x16x32_bf16 v[4:7], v[174:177], v[206:209], v[4:7]
	v_mfma_f32_16x16x32_bf16 v[20:23], v[170:173], v[194:197], v[20:23]
	v_mfma_f32_16x16x32_bf16 v[20:23], v[174:177], v[198:201], v[20:23]
	v_mfma_f32_16x16x32_bf16 v[36:39], v[170:173], v[186:189], v[36:39]
	v_mfma_f32_16x16x32_bf16 v[36:39], v[174:177], v[190:193], v[36:39]
	v_mfma_f32_16x16x32_bf16 v[52:55], v[170:173], v[178:181], v[52:55]
	v_mfma_f32_16x16x32_bf16 v[52:55], v[174:177], v[182:185], v[52:55]
	s_setprio 0
	s_barrier
	v_add_u32_e32 v158, s49, v144
	v_add_u32_e32 v174, s56, v144
	ds_read_b128 v[146:149], v158
	ds_read_b128 v[150:153], v158 offset:1024
	ds_read_b128 v[154:157], v158 offset:2048
	ds_read_b128 v[158:161], v158 offset:3072
	ds_read_b128 v[162:165], v174
	ds_read_b128 v[166:169], v174 offset:1024
	ds_read_b128 v[170:173], v174 offset:2048
	ds_read_b128 v[174:177], v174 offset:3072
	s_add_u32 s38, s38, 0x80000
	s_addc_u32 s39, s39, 0
	s_mov_b32 m0, s45
	v_lshl_add_u64 v[216:217], s[38:39], 0, v[136:137]
	ds_read_b128 v[178:181], v145 offset:32768
	ds_read_b128 v[182:185], v145 offset:33792
	ds_read_b128 v[186:189], v145 offset:34816
	ds_read_b128 v[190:193], v145 offset:35840
	ds_read_b128 v[194:197], v145 offset:36864
	ds_read_b128 v[198:201], v145 offset:37888
	ds_read_b128 v[202:205], v145 offset:38912
	ds_read_b128 v[206:209], v145 offset:39936
	global_load_lds_dwordx4 v[216:217], off
	v_lshl_add_u64 v[216:217], s[38:39], 0, v[134:135]
	s_mov_b32 m0, s46
	s_nop 0
	global_load_lds_dwordx4 v[216:217], off
	s_waitcnt vmcnt(8)
	s_waitcnt lgkmcnt(0)
	s_barrier
	s_setprio 1
	s_waitcnt lgkmcnt(0)
	v_mfma_f32_16x16x32_bf16 v[128:131], v[146:149], v[178:181], v[128:131]
	v_mfma_f32_16x16x32_bf16 v[128:131], v[150:153], v[182:185], v[128:131]
	v_mfma_f32_16x16x32_bf16 v[112:115], v[146:149], v[186:189], v[112:115]
	v_mfma_f32_16x16x32_bf16 v[112:115], v[150:153], v[190:193], v[112:115]
	v_mfma_f32_16x16x32_bf16 v[96:99], v[146:149], v[194:197], v[96:99]
	v_mfma_f32_16x16x32_bf16 v[96:99], v[150:153], v[198:201], v[96:99]
	v_mfma_f32_16x16x32_bf16 v[80:83], v[146:149], v[202:205], v[80:83]
	v_mfma_f32_16x16x32_bf16 v[80:83], v[150:153], v[206:209], v[80:83]
	v_mfma_f32_16x16x32_bf16 v[72:75], v[154:157], v[202:205], v[72:75]
	v_mfma_f32_16x16x32_bf16 v[72:75], v[158:161], v[206:209], v[72:75]
	v_mfma_f32_16x16x32_bf16 v[88:91], v[154:157], v[194:197], v[88:91]
	v_mfma_f32_16x16x32_bf16 v[88:91], v[158:161], v[198:201], v[88:91]
	v_mfma_f32_16x16x32_bf16 v[104:107], v[154:157], v[186:189], v[104:107]
	v_mfma_f32_16x16x32_bf16 v[104:107], v[158:161], v[190:193], v[104:107]
	v_mfma_f32_16x16x32_bf16 v[120:123], v[154:157], v[178:181], v[120:123]
	v_mfma_f32_16x16x32_bf16 v[120:123], v[158:161], v[182:185], v[120:123]
	s_setprio 0
	s_setprio 1
	v_mfma_f32_16x16x32_bf16 v[124:127], v[162:165], v[178:181], v[124:127]
	v_mfma_f32_16x16x32_bf16 v[124:127], v[166:169], v[182:185], v[124:127]
	v_mfma_f32_16x16x32_bf16 v[108:111], v[162:165], v[186:189], v[108:111]
	v_mfma_f32_16x16x32_bf16 v[108:111], v[166:169], v[190:193], v[108:111]
	v_mfma_f32_16x16x32_bf16 v[92:95], v[162:165], v[194:197], v[92:95]
	v_mfma_f32_16x16x32_bf16 v[92:95], v[166:169], v[198:201], v[92:95]
	v_mfma_f32_16x16x32_bf16 v[76:79], v[162:165], v[202:205], v[76:79]
	v_mfma_f32_16x16x32_bf16 v[76:79], v[166:169], v[206:209], v[76:79]
	v_mfma_f32_16x16x32_bf16 v[68:71], v[170:173], v[202:205], v[68:71]
	v_mfma_f32_16x16x32_bf16 v[68:71], v[174:177], v[206:209], v[68:71]
	v_mfma_f32_16x16x32_bf16 v[84:87], v[170:173], v[194:197], v[84:87]
	v_mfma_f32_16x16x32_bf16 v[84:87], v[174:177], v[198:201], v[84:87]
	v_mfma_f32_16x16x32_bf16 v[100:103], v[170:173], v[186:189], v[100:103]
	v_mfma_f32_16x16x32_bf16 v[100:103], v[174:177], v[190:193], v[100:103]
	v_mfma_f32_16x16x32_bf16 v[116:119], v[170:173], v[178:181], v[116:119]
	v_mfma_f32_16x16x32_bf16 v[116:119], v[174:177], v[182:185], v[116:119]
	s_setprio 0
	s_barrier
	s_mov_b32 m0, s50
	v_lshl_add_u64 v[142:143], v[142:143], 0, s[64:65]
	s_add_u32 s18, s18, 0x80080
	ds_read_b128 v[178:181], v145 offset:49152
	ds_read_b128 v[182:185], v145 offset:50176
	ds_read_b128 v[186:189], v145 offset:51200
	ds_read_b128 v[190:193], v145 offset:52224
	ds_read_b128 v[194:197], v145 offset:53248
	ds_read_b128 v[198:201], v145 offset:54272
	ds_read_b128 v[202:205], v145 offset:55296
	ds_read_b128 v[206:209], v145 offset:56320
	global_load_lds_dwordx4 v[142:143], off
	v_lshl_add_u64 v[142:143], v[210:211], 0, s[64:65]
	s_mov_b32 m0, s51
	s_addc_u32 s19, s19, 0
	global_load_lds_dwordx4 v[142:143], off
	v_lshl_add_u64 v[142:143], s[18:19], 0, v[2:3]
	s_mov_b32 m0, s57
	s_nop 0
	global_load_lds_dwordx4 v[142:143], off
	v_lshl_add_u64 v[142:143], s[18:19], 0, v[132:133]
	s_mov_b32 m0, s58
	s_nop 0
	global_load_lds_dwordx4 v[142:143], off
	v_lshl_add_u64 v[142:143], v[212:213], 0, s[64:65]
	s_mov_b32 m0, s52
	s_nop 0
	global_load_lds_dwordx4 v[142:143], off
	v_lshl_add_u64 v[142:143], v[214:215], 0, s[64:65]
	s_mov_b32 m0, s53
	s_nop 0
	global_load_lds_dwordx4 v[142:143], off
	s_waitcnt vmcnt(8)
	s_waitcnt lgkmcnt(0)
	s_barrier
	s_setprio 1
	s_waitcnt lgkmcnt(0)
	v_mfma_f32_16x16x32_bf16 v[64:67], v[146:149], v[178:181], v[64:67]
	v_mfma_f32_16x16x32_bf16 v[64:67], v[150:153], v[182:185], v[64:67]
	v_mfma_f32_16x16x32_bf16 v[48:51], v[146:149], v[186:189], v[48:51]
	v_mfma_f32_16x16x32_bf16 v[48:51], v[150:153], v[190:193], v[48:51]
	v_mfma_f32_16x16x32_bf16 v[32:35], v[146:149], v[194:197], v[32:35]
	v_mfma_f32_16x16x32_bf16 v[32:35], v[150:153], v[198:201], v[32:35]
	v_mfma_f32_16x16x32_bf16 v[16:19], v[146:149], v[202:205], v[16:19]
	v_mfma_f32_16x16x32_bf16 v[16:19], v[150:153], v[206:209], v[16:19]
	v_mfma_f32_16x16x32_bf16 v[8:11], v[154:157], v[202:205], v[8:11]
	v_mfma_f32_16x16x32_bf16 v[8:11], v[158:161], v[206:209], v[8:11]
	v_mfma_f32_16x16x32_bf16 v[24:27], v[154:157], v[194:197], v[24:27]
	v_mfma_f32_16x16x32_bf16 v[24:27], v[158:161], v[198:201], v[24:27]
	v_mfma_f32_16x16x32_bf16 v[40:43], v[154:157], v[186:189], v[40:43]
	v_mfma_f32_16x16x32_bf16 v[40:43], v[158:161], v[190:193], v[40:43]
	v_mfma_f32_16x16x32_bf16 v[56:59], v[154:157], v[178:181], v[56:59]
	v_mfma_f32_16x16x32_bf16 v[56:59], v[158:161], v[182:185], v[56:59]
	s_setprio 0
	s_setprio 1
	v_mfma_f32_16x16x32_bf16 v[60:63], v[162:165], v[178:181], v[60:63]
	v_mfma_f32_16x16x32_bf16 v[60:63], v[166:169], v[182:185], v[60:63]
	v_mfma_f32_16x16x32_bf16 v[44:47], v[162:165], v[186:189], v[44:47]
	v_mfma_f32_16x16x32_bf16 v[44:47], v[166:169], v[190:193], v[44:47]
	v_mfma_f32_16x16x32_bf16 v[28:31], v[162:165], v[194:197], v[28:31]
	v_mfma_f32_16x16x32_bf16 v[28:31], v[166:169], v[198:201], v[28:31]
	v_mfma_f32_16x16x32_bf16 v[12:15], v[162:165], v[202:205], v[12:15]
	v_mfma_f32_16x16x32_bf16 v[12:15], v[166:169], v[206:209], v[12:15]
	v_mfma_f32_16x16x32_bf16 v[4:7], v[170:173], v[202:205], v[4:7]
	v_mfma_f32_16x16x32_bf16 v[4:7], v[174:177], v[206:209], v[4:7]
	v_mfma_f32_16x16x32_bf16 v[20:23], v[170:173], v[194:197], v[20:23]
	v_mfma_f32_16x16x32_bf16 v[20:23], v[174:177], v[198:201], v[20:23]
	v_mfma_f32_16x16x32_bf16 v[36:39], v[170:173], v[186:189], v[36:39]
	v_mfma_f32_16x16x32_bf16 v[36:39], v[174:177], v[190:193], v[36:39]
	v_mfma_f32_16x16x32_bf16 v[52:55], v[170:173], v[178:181], v[52:55]
	v_mfma_f32_16x16x32_bf16 v[52:55], v[174:177], v[182:185], v[52:55]
	s_setprio 0
	s_barrier
	s_add_i32 s74, s74, 2
	s_add_u32 s34, s34, 0x100
	s_addc_u32 s35, s35, 0
	s_add_u32 s71, s71, 0x100
	s_addc_u32 s73, s73, 0
	s_cmp_gt_u32 s74, 29
	s_cbranch_scc0 .LBB0_3116
	s_and_b64 vcc, exec, s[8:9]
	s_cbranch_vccz .LBB0_3119
	s_barrier

.LBB0_3195:
	v_add_u32_e32 v144, s26, v249
	v_add_u32_e32 v160, s38, v249
	ds_read_b128 v[132:135], v144
	ds_read_b128 v[136:139], v144 offset:1024
	ds_read_b128 v[140:143], v144 offset:2048
	ds_read_b128 v[144:147], v144 offset:3072
	ds_read_b128 v[148:151], v160
	ds_read_b128 v[152:155], v160 offset:1024
	ds_read_b128 v[156:159], v160 offset:2048
	ds_read_b128 v[160:163], v160 offset:3072
	s_add_u32 s24, s14, 0x100
	s_addc_u32 s25, s15, 0
	s_cmpk_eq_i32 s74, 0x54
	s_cselect_b32 s35, s5, s25
	s_cselect_b32 s34, s4, s24
	s_cselect_b32 s19, s13, s73
	s_cselect_b32 s18, s12, s71
	v_lshl_add_u64 v[196:197], s[14:15], 0, v[222:223]
	s_add_i32 m0, s41, 0xc000
	ds_read_b128 v[164:167], v250
	ds_read_b128 v[168:171], v250 offset:1024
	ds_read_b128 v[172:175], v250 offset:2048
	ds_read_b128 v[176:179], v250 offset:3072
	ds_read_b128 v[180:183], v250 offset:4096
	ds_read_b128 v[184:187], v250 offset:5120
	ds_read_b128 v[188:191], v250 offset:6144
	ds_read_b128 v[192:195], v250 offset:7168
	global_load_lds_dwordx4 v[196:197], off
	v_lshl_add_u64 v[196:197], s[14:15], 0, v[224:225]
	s_add_i32 m0, s41, 0xe000
	s_nop 0
	global_load_lds_dwordx4 v[196:197], off
	s_waitcnt vmcnt(8)
	s_waitcnt lgkmcnt(0)
	s_barrier
	s_setprio 1
	s_waitcnt lgkmcnt(0)
	v_mfma_f32_16x16x32_bf16 v[128:131], v[132:135], v[164:167], v[128:131]
	v_mfma_f32_16x16x32_bf16 v[128:131], v[136:139], v[168:171], v[128:131]
	v_mfma_f32_16x16x32_bf16 v[112:115], v[132:135], v[172:175], v[112:115]
	v_mfma_f32_16x16x32_bf16 v[112:115], v[136:139], v[176:179], v[112:115]
	v_mfma_f32_16x16x32_bf16 v[96:99], v[132:135], v[180:183], v[96:99]
	v_mfma_f32_16x16x32_bf16 v[96:99], v[136:139], v[184:187], v[96:99]
	v_mfma_f32_16x16x32_bf16 v[80:83], v[132:135], v[188:191], v[80:83]
	v_mfma_f32_16x16x32_bf16 v[80:83], v[136:139], v[192:195], v[80:83]
	v_mfma_f32_16x16x32_bf16 v[76:79], v[140:143], v[188:191], v[76:79]
	v_mfma_f32_16x16x32_bf16 v[76:79], v[144:147], v[192:195], v[76:79]
	v_mfma_f32_16x16x32_bf16 v[92:95], v[140:143], v[180:183], v[92:95]
	v_mfma_f32_16x16x32_bf16 v[92:95], v[144:147], v[184:187], v[92:95]
	v_mfma_f32_16x16x32_bf16 v[108:111], v[140:143], v[172:175], v[108:111]
	v_mfma_f32_16x16x32_bf16 v[108:111], v[144:147], v[176:179], v[108:111]
	v_mfma_f32_16x16x32_bf16 v[124:127], v[140:143], v[164:167], v[124:127]
	v_mfma_f32_16x16x32_bf16 v[124:127], v[144:147], v[168:171], v[124:127]
	s_setprio 0
	s_setprio 1
	v_mfma_f32_16x16x32_bf16 v[120:123], v[148:151], v[164:167], v[120:123]
	v_mfma_f32_16x16x32_bf16 v[120:123], v[152:155], v[168:171], v[120:123]
	v_mfma_f32_16x16x32_bf16 v[104:107], v[148:151], v[172:175], v[104:107]
	v_mfma_f32_16x16x32_bf16 v[104:107], v[152:155], v[176:179], v[104:107]
	v_mfma_f32_16x16x32_bf16 v[88:91], v[148:151], v[180:183], v[88:91]
	v_mfma_f32_16x16x32_bf16 v[88:91], v[152:155], v[184:187], v[88:91]
	v_mfma_f32_16x16x32_bf16 v[72:75], v[148:151], v[188:191], v[72:75]
	v_mfma_f32_16x16x32_bf16 v[72:75], v[152:155], v[192:195], v[72:75]
	v_mfma_f32_16x16x32_bf16 v[68:71], v[156:159], v[188:191], v[68:71]
	v_mfma_f32_16x16x32_bf16 v[68:71], v[160:163], v[192:195], v[68:71]
	v_mfma_f32_16x16x32_bf16 v[84:87], v[156:159], v[180:183], v[84:87]
	v_mfma_f32_16x16x32_bf16 v[84:87], v[160:163], v[184:187], v[84:87]
	v_mfma_f32_16x16x32_bf16 v[100:103], v[156:159], v[172:175], v[100:103]
	v_mfma_f32_16x16x32_bf16 v[100:103], v[160:163], v[176:179], v[100:103]
	v_mfma_f32_16x16x32_bf16 v[116:119], v[156:159], v[164:167], v[116:119]
	v_mfma_f32_16x16x32_bf16 v[116:119], v[160:163], v[168:171], v[116:119]
	s_setprio 0
	s_barrier
	s_mov_b32 m0, s27
	v_lshl_add_u64 v[196:197], s[18:19], 0, v[2:3]
	s_add_u32 s14, s18, 0x160000
	ds_read_b128 v[164:167], v250 offset:16384
	ds_read_b128 v[168:171], v250 offset:17408
	ds_read_b128 v[172:175], v250 offset:18432
	ds_read_b128 v[176:179], v250 offset:19456
	ds_read_b128 v[180:183], v250 offset:20480
	ds_read_b128 v[184:187], v250 offset:21504
	ds_read_b128 v[188:191], v250 offset:22528
	ds_read_b128 v[192:195], v250 offset:23552
	global_load_lds_dwordx4 v[196:197], off
	v_lshl_add_u64 v[198:199], s[18:19], 0, v[216:217]
	s_mov_b32 m0, s37
	s_addc_u32 s15, s19, 0
	global_load_lds_dwordx4 v[198:199], off
	v_lshl_add_u64 v[200:201], s[14:15], 0, v[2:3]
	s_mov_b32 m0, s39
	v_lshl_add_u64 v[202:203], s[34:35], 0, v[218:219]
	global_load_lds_dwordx4 v[200:201], off
	v_lshl_add_u64 v[200:201], s[14:15], 0, v[216:217]
	s_mov_b32 m0, s40
	s_nop 0
	global_load_lds_dwordx4 v[200:201], off
	v_lshl_add_u64 v[200:201], s[34:35], 0, v[220:221]
	s_mov_b32 m0, s41
	s_nop 0
	global_load_lds_dwordx4 v[200:201], off
	s_mov_b32 m0, s42
	s_nop 0
	global_load_lds_dwordx4 v[202:203], off
	s_waitcnt vmcnt(8)
	s_waitcnt lgkmcnt(0)
	s_barrier
	s_setprio 1
	s_waitcnt lgkmcnt(0)
	v_mfma_f32_16x16x32_bf16 v[64:67], v[132:135], v[164:167], v[64:67]
	v_mfma_f32_16x16x32_bf16 v[64:67], v[136:139], v[168:171], v[64:67]
	v_mfma_f32_16x16x32_bf16 v[48:51], v[132:135], v[172:175], v[48:51]
	v_mfma_f32_16x16x32_bf16 v[48:51], v[136:139], v[176:179], v[48:51]
	v_mfma_f32_16x16x32_bf16 v[32:35], v[132:135], v[180:183], v[32:35]
	v_mfma_f32_16x16x32_bf16 v[32:35], v[136:139], v[184:187], v[32:35]
	v_mfma_f32_16x16x32_bf16 v[16:19], v[132:135], v[188:191], v[16:19]
	v_mfma_f32_16x16x32_bf16 v[16:19], v[136:139], v[192:195], v[16:19]
	v_mfma_f32_16x16x32_bf16 v[12:15], v[140:143], v[188:191], v[12:15]
	v_mfma_f32_16x16x32_bf16 v[12:15], v[144:147], v[192:195], v[12:15]
	v_mfma_f32_16x16x32_bf16 v[28:31], v[140:143], v[180:183], v[28:31]
	v_mfma_f32_16x16x32_bf16 v[28:31], v[144:147], v[184:187], v[28:31]
	v_mfma_f32_16x16x32_bf16 v[44:47], v[140:143], v[172:175], v[44:47]
	v_mfma_f32_16x16x32_bf16 v[44:47], v[144:147], v[176:179], v[44:47]
	v_mfma_f32_16x16x32_bf16 v[60:63], v[140:143], v[164:167], v[60:63]
	v_mfma_f32_16x16x32_bf16 v[60:63], v[144:147], v[168:171], v[60:63]
	s_setprio 0
	s_setprio 1
	v_mfma_f32_16x16x32_bf16 v[56:59], v[148:151], v[164:167], v[56:59]
	v_mfma_f32_16x16x32_bf16 v[56:59], v[152:155], v[168:171], v[56:59]
	v_mfma_f32_16x16x32_bf16 v[40:43], v[148:151], v[172:175], v[40:43]
	v_mfma_f32_16x16x32_bf16 v[40:43], v[152:155], v[176:179], v[40:43]
	v_mfma_f32_16x16x32_bf16 v[24:27], v[148:151], v[180:183], v[24:27]
	v_mfma_f32_16x16x32_bf16 v[24:27], v[152:155], v[184:187], v[24:27]
	v_mfma_f32_16x16x32_bf16 v[8:11], v[148:151], v[188:191], v[8:11]
	v_mfma_f32_16x16x32_bf16 v[8:11], v[152:155], v[192:195], v[8:11]
	v_mfma_f32_16x16x32_bf16 v[4:7], v[156:159], v[188:191], v[4:7]
	v_mfma_f32_16x16x32_bf16 v[4:7], v[160:163], v[192:195], v[4:7]
	v_mfma_f32_16x16x32_bf16 v[20:23], v[156:159], v[180:183], v[20:23]
	v_mfma_f32_16x16x32_bf16 v[20:23], v[160:163], v[184:187], v[20:23]
	v_mfma_f32_16x16x32_bf16 v[36:39], v[156:159], v[172:175], v[36:39]
	v_mfma_f32_16x16x32_bf16 v[36:39], v[160:163], v[176:179], v[36:39]
	v_mfma_f32_16x16x32_bf16 v[52:55], v[156:159], v[164:167], v[52:55]
	v_mfma_f32_16x16x32_bf16 v[52:55], v[160:163], v[168:171], v[52:55]
	s_setprio 0
	s_barrier
	v_add_u32_e32 v144, s49, v249
	v_add_u32_e32 v160, s56, v249
	ds_read_b128 v[132:135], v144
	ds_read_b128 v[136:139], v144 offset:1024
	ds_read_b128 v[140:143], v144 offset:2048
	ds_read_b128 v[144:147], v144 offset:3072
	ds_read_b128 v[148:151], v160
	ds_read_b128 v[152:155], v160 offset:1024
	ds_read_b128 v[156:159], v160 offset:2048
	ds_read_b128 v[160:163], v160 offset:3072
	s_add_u32 s14, s34, 0x160000
	s_addc_u32 s15, s35, 0
	s_mov_b32 m0, s43
	v_lshl_add_u64 v[204:205], s[14:15], 0, v[220:221]
	ds_read_b128 v[164:167], v250 offset:32768
	ds_read_b128 v[168:171], v250 offset:33792
	ds_read_b128 v[172:175], v250 offset:34816
	ds_read_b128 v[176:179], v250 offset:35840
	ds_read_b128 v[180:183], v250 offset:36864
	ds_read_b128 v[184:187], v250 offset:37888
	ds_read_b128 v[188:191], v250 offset:38912
	ds_read_b128 v[192:195], v250 offset:39936
	global_load_lds_dwordx4 v[204:205], off
	v_lshl_add_u64 v[204:205], s[14:15], 0, v[218:219]
	s_mov_b32 m0, s44
	s_nop 0
	global_load_lds_dwordx4 v[204:205], off
	s_waitcnt vmcnt(8)
	s_waitcnt lgkmcnt(0)
	s_barrier
	s_setprio 1
	s_waitcnt lgkmcnt(0)
	v_mfma_f32_16x16x32_bf16 v[128:131], v[132:135], v[164:167], v[128:131]
	v_mfma_f32_16x16x32_bf16 v[128:131], v[136:139], v[168:171], v[128:131]
	v_mfma_f32_16x16x32_bf16 v[112:115], v[132:135], v[172:175], v[112:115]
	v_mfma_f32_16x16x32_bf16 v[112:115], v[136:139], v[176:179], v[112:115]
	v_mfma_f32_16x16x32_bf16 v[96:99], v[132:135], v[180:183], v[96:99]
	v_mfma_f32_16x16x32_bf16 v[96:99], v[136:139], v[184:187], v[96:99]
	v_mfma_f32_16x16x32_bf16 v[80:83], v[132:135], v[188:191], v[80:83]
	v_mfma_f32_16x16x32_bf16 v[80:83], v[136:139], v[192:195], v[80:83]
	v_mfma_f32_16x16x32_bf16 v[76:79], v[140:143], v[188:191], v[76:79]
	v_mfma_f32_16x16x32_bf16 v[76:79], v[144:147], v[192:195], v[76:79]
	v_mfma_f32_16x16x32_bf16 v[92:95], v[140:143], v[180:183], v[92:95]
	v_mfma_f32_16x16x32_bf16 v[92:95], v[144:147], v[184:187], v[92:95]
	v_mfma_f32_16x16x32_bf16 v[108:111], v[140:143], v[172:175], v[108:111]
	v_mfma_f32_16x16x32_bf16 v[108:111], v[144:147], v[176:179], v[108:111]
	v_mfma_f32_16x16x32_bf16 v[124:127], v[140:143], v[164:167], v[124:127]
	v_mfma_f32_16x16x32_bf16 v[124:127], v[144:147], v[168:171], v[124:127]
	s_setprio 0
	s_setprio 1
	v_mfma_f32_16x16x32_bf16 v[120:123], v[148:151], v[164:167], v[120:123]
	v_mfma_f32_16x16x32_bf16 v[120:123], v[152:155], v[168:171], v[120:123]
	v_mfma_f32_16x16x32_bf16 v[104:107], v[148:151], v[172:175], v[104:107]
	v_mfma_f32_16x16x32_bf16 v[104:107], v[152:155], v[176:179], v[104:107]
	v_mfma_f32_16x16x32_bf16 v[88:91], v[148:151], v[180:183], v[88:91]
	v_mfma_f32_16x16x32_bf16 v[88:91], v[152:155], v[184:187], v[88:91]
	v_mfma_f32_16x16x32_bf16 v[72:75], v[148:151], v[188:191], v[72:75]
	v_mfma_f32_16x16x32_bf16 v[72:75], v[152:155], v[192:195], v[72:75]
	v_mfma_f32_16x16x32_bf16 v[68:71], v[156:159], v[188:191], v[68:71]
	v_mfma_f32_16x16x32_bf16 v[68:71], v[160:163], v[192:195], v[68:71]
	v_mfma_f32_16x16x32_bf16 v[84:87], v[156:159], v[180:183], v[84:87]
	v_mfma_f32_16x16x32_bf16 v[84:87], v[160:163], v[184:187], v[84:87]
	v_mfma_f32_16x16x32_bf16 v[100:103], v[156:159], v[172:175], v[100:103]
	v_mfma_f32_16x16x32_bf16 v[100:103], v[160:163], v[176:179], v[100:103]
	v_mfma_f32_16x16x32_bf16 v[116:119], v[156:159], v[164:167], v[116:119]
	v_mfma_f32_16x16x32_bf16 v[116:119], v[160:163], v[168:171], v[116:119]
	s_setprio 0
	s_barrier
	s_mov_b32 m0, s50
	v_lshl_add_u64 v[196:197], v[196:197], 0, s[64:65]
	s_add_u32 s14, s18, 0x160080
	ds_read_b128 v[164:167], v250 offset:49152
	ds_read_b128 v[168:171], v250 offset:50176
	ds_read_b128 v[172:175], v250 offset:51200
	ds_read_b128 v[176:179], v250 offset:52224
	ds_read_b128 v[180:183], v250 offset:53248
	ds_read_b128 v[184:187], v250 offset:54272
	ds_read_b128 v[188:191], v250 offset:55296
	ds_read_b128 v[192:195], v250 offset:56320
	global_load_lds_dwordx4 v[196:197], off
	v_lshl_add_u64 v[196:197], v[198:199], 0, s[64:65]
	s_mov_b32 m0, s51
	s_addc_u32 s15, s19, 0
	global_load_lds_dwordx4 v[196:197], off
	v_lshl_add_u64 v[196:197], s[14:15], 0, v[2:3]
	s_mov_b32 m0, s57
	s_nop 0
	global_load_lds_dwordx4 v[196:197], off
	v_lshl_add_u64 v[196:197], s[14:15], 0, v[216:217]
	s_mov_b32 m0, s58
	s_nop 0
	global_load_lds_dwordx4 v[196:197], off
	v_lshl_add_u64 v[196:197], v[200:201], 0, s[64:65]
	s_mov_b32 m0, s52
	s_nop 0
	global_load_lds_dwordx4 v[196:197], off
	v_lshl_add_u64 v[196:197], v[202:203], 0, s[64:65]
	s_mov_b32 m0, s53
	s_nop 0
	global_load_lds_dwordx4 v[196:197], off
	s_waitcnt vmcnt(8)
	s_waitcnt lgkmcnt(0)
	s_barrier
	s_setprio 1
	s_waitcnt lgkmcnt(0)
	v_mfma_f32_16x16x32_bf16 v[64:67], v[132:135], v[164:167], v[64:67]
	v_mfma_f32_16x16x32_bf16 v[64:67], v[136:139], v[168:171], v[64:67]
	v_mfma_f32_16x16x32_bf16 v[48:51], v[132:135], v[172:175], v[48:51]
	v_mfma_f32_16x16x32_bf16 v[48:51], v[136:139], v[176:179], v[48:51]
	v_mfma_f32_16x16x32_bf16 v[32:35], v[132:135], v[180:183], v[32:35]
	v_mfma_f32_16x16x32_bf16 v[32:35], v[136:139], v[184:187], v[32:35]
	v_mfma_f32_16x16x32_bf16 v[16:19], v[132:135], v[188:191], v[16:19]
	v_mfma_f32_16x16x32_bf16 v[16:19], v[136:139], v[192:195], v[16:19]
	v_mfma_f32_16x16x32_bf16 v[12:15], v[140:143], v[188:191], v[12:15]
	v_mfma_f32_16x16x32_bf16 v[12:15], v[144:147], v[192:195], v[12:15]
	v_mfma_f32_16x16x32_bf16 v[28:31], v[140:143], v[180:183], v[28:31]
	v_mfma_f32_16x16x32_bf16 v[28:31], v[144:147], v[184:187], v[28:31]
	v_mfma_f32_16x16x32_bf16 v[44:47], v[140:143], v[172:175], v[44:47]
	v_mfma_f32_16x16x32_bf16 v[44:47], v[144:147], v[176:179], v[44:47]
	v_mfma_f32_16x16x32_bf16 v[60:63], v[140:143], v[164:167], v[60:63]
	v_mfma_f32_16x16x32_bf16 v[60:63], v[144:147], v[168:171], v[60:63]
	s_setprio 0
	s_setprio 1
	v_mfma_f32_16x16x32_bf16 v[56:59], v[148:151], v[164:167], v[56:59]
	v_mfma_f32_16x16x32_bf16 v[56:59], v[152:155], v[168:171], v[56:59]
	v_mfma_f32_16x16x32_bf16 v[40:43], v[148:151], v[172:175], v[40:43]
	v_mfma_f32_16x16x32_bf16 v[40:43], v[152:155], v[176:179], v[40:43]
	v_mfma_f32_16x16x32_bf16 v[24:27], v[148:151], v[180:183], v[24:27]
	v_mfma_f32_16x16x32_bf16 v[24:27], v[152:155], v[184:187], v[24:27]
	v_mfma_f32_16x16x32_bf16 v[8:11], v[148:151], v[188:191], v[8:11]
	v_mfma_f32_16x16x32_bf16 v[8:11], v[152:155], v[192:195], v[8:11]
	v_mfma_f32_16x16x32_bf16 v[4:7], v[156:159], v[188:191], v[4:7]
	v_mfma_f32_16x16x32_bf16 v[4:7], v[160:163], v[192:195], v[4:7]
	v_mfma_f32_16x16x32_bf16 v[20:23], v[156:159], v[180:183], v[20:23]
	v_mfma_f32_16x16x32_bf16 v[20:23], v[160:163], v[184:187], v[20:23]
	v_mfma_f32_16x16x32_bf16 v[36:39], v[156:159], v[172:175], v[36:39]
	v_mfma_f32_16x16x32_bf16 v[36:39], v[160:163], v[176:179], v[36:39]
	v_mfma_f32_16x16x32_bf16 v[52:55], v[156:159], v[164:167], v[52:55]
	v_mfma_f32_16x16x32_bf16 v[52:55], v[160:163], v[168:171], v[52:55]
	s_setprio 0
	s_barrier
	s_add_i32 s74, s74, 2
	s_add_u32 s71, s71, 0x100
	s_addc_u32 s73, s73, 0
	s_cmpk_gt_u32 s74, 0x55
	s_mov_b64 s[14:15], s[24:25]
	s_cbranch_scc0 .LBB0_3195
	s_and_b64 vcc, exec, s[10:11]
	s_cbranch_vccz .LBB0_3198
	s_barrier
